# GEMM K-loops: the wait state between an M0 write and its LDS-DMA piece is filled by one of the segment's own ds_reads instead of an s_nop (7 per K-iteration)
# speedup vs baseline: 1.0038x; 1.0038x over previous
; #define PG8_STAGE(bufoff, gbase, voff) do { _Pragma("unroll") for (int _i = 0; _i < 2; ++_i) \
;         __builtin_amdgcn_global_load_lds((const unsigned*)((const char*)(gbase) + (voff)[_i]), (PG8_LAS unsigned*)(lds + (bufoff) + ldsw + _i * 8192), 16, 0, 0); } while (0)
; #define PG8_LDA(dst, b, h) do { _Pragma("unroll") for (int m = 0; m < 4; ++m) _Pragma("unroll") for (int k = 0; k < 2; ++k) dst[m][k] = *(const PG8_LAS bf16x8*)(lds + PG8_SA(b, h) + aoff + m * 2048 + k * 1024); } while (0)
; #define PG8_LDB(dst, b, h) do { _Pragma("unroll") for (int n = 0; n < 2; ++n) _Pragma("unroll") for (int k = 0; k < 2; ++k) dst[n][k] = *(const PG8_LAS bf16x8*)(lds + PG8_SB(b, h) + boff + n * 2048 + k * 1024); } while (0)
; #define PG8_MMA(ai, bj, At, Bt) do { __builtin_amdgcn_s_setprio(1); _Pragma("unroll") for (int m = 0; m < 4; ++m) _Pragma("unroll") for (int n = 0; n < 2; ++n) _Pragma("unroll") for (int k = 0; k < 2; ++k) \
;         acc[ai][bj][m][n] = __builtin_amdgcn_mfma_f32_16x16x32_bf16(Bt[n][k], At[m][k], acc[ai][bj][m][n], 0, 0, 0); __builtin_amdgcn_s_setprio(0); } while (0)
; #define PG8_WAIT_V(n) asm volatile("s_waitcnt vmcnt(" #n ")" ::: "memory")
; template <class Epi, class Sched>
; __device__ __forceinline__ void gemm_phase(PG8_LAS unsigned char* lds, const Gemm g, const Sched& S, const Epi& E) {
;     ...
;         for (int t = 0; t < nt; t += 2) {
;             const bool last = (t == nt - 2);
;             const char* a1 = cA + (size_t)(t + 1) * kstep;
;             const char* a2 = last ? nA : cA + (size_t)(t + 2) * kstep; const char* b2 = last ? nB : cB + (size_t)(t + 2) * kstep;
;             const char* a3 = a2 + kstep; const char* b3 = b2 + kstep;
;             if (last && has_next) S.a_ready(nxt);
;             PG8_LDB(B0, 0, 0); PG8_SCHED; PG8_LDA(At, 0, 0); PG8_STAGE(PG8_SA(1, 1), a1 + hstep, voffA);
;             PG8_WAIT_L(8); PG8_BAR; PG8_WAIT_L(0); PG8_MMA(0, 0, At, B0); PG8_BAR; PG8_SCHED;
;             PG8_LDB(B1, 0, 1); PG8_STAGE(PG8_SB(0, 0), b2, voffB);
;             PG8_BAR; PG8_WAIT_L(0); PG8_MMA(0, 1, At, B1); PG8_BAR;
;             PG8_LDA(At, 0, 1); PG8_STAGE(PG8_SA(0, 0), a2, voffA);
;             PG8_BAR; PG8_WAIT_L(0); PG8_MMA(1, 0, At, B0); PG8_BAR; PG8_SCHED;
;             PG8_STAGE(PG8_SB(0, 1), b2 + hstep, voffB);
;             PG8_WAIT_V(6); PG8_BAR; PG8_MMA(1, 1, At, B1); PG8_BAR;
.LBB0_96:
	s_add_u32 s10, s8, 0x100
	s_addc_u32 s11, s9, 0
	v_add_u32_e32 v154, 0x10000, v139
	ds_read_b128 v[142:145], v154
	ds_read_b128 v[146:149], v154 offset:1024
	ds_read_b128 v[150:153], v154 offset:2048
	ds_read_b128 v[154:157], v154 offset:3072
	s_cmp_eq_u32 s45, 40
	s_cselect_b32 s15, s1, s11
	s_cselect_b32 s14, s0, s10
	s_cselect_b32 s13, s5, s44
	s_cselect_b32 s12, s4, s43
	s_add_i32 m0, s20, 0xc000
	ds_read_b128 v[158:161], v141
	ds_read_b128 v[162:165], v141 offset:1024
	ds_read_b128 v[166:169], v141 offset:2048
	ds_read_b128 v[170:173], v141 offset:3072
	ds_read_b128 v[178:181], v141 offset:4096
	ds_read_b128 v[182:185], v141 offset:5120
	ds_read_b128 v[186:189], v141 offset:6144
	global_load_lds_dwordx4 v134, s[8:9]
	s_add_i32 m0, s20, 0xe000
	ds_read_b128 v[190:193], v141 offset:7168
	global_load_lds_dwordx4 v136, s[8:9]
	s_waitcnt lgkmcnt(8)
	s_barrier
	s_waitcnt lgkmcnt(0)
	v_mfma_f32_16x16x32_bf16 v[124:127], v[142:145], v[158:161], v[124:127]
	v_mfma_f32_16x16x32_bf16 v[120:123], v[150:153], v[158:161], v[120:123]
	v_mfma_f32_16x16x32_bf16 v[116:119], v[142:145], v[166:169], v[116:119]
	v_mfma_f32_16x16x32_bf16 v[112:115], v[150:153], v[166:169], v[112:115]
	v_mfma_f32_16x16x32_bf16 v[100:103], v[142:145], v[178:181], v[100:103]
	v_mfma_f32_16x16x32_bf16 v[96:99], v[150:153], v[178:181], v[96:99]
	v_mfma_f32_16x16x32_bf16 v[84:87], v[142:145], v[186:189], v[84:87]
	v_mfma_f32_16x16x32_bf16 v[80:83], v[150:153], v[186:189], v[80:83]
	v_mfma_f32_16x16x32_bf16 v[124:127], v[146:149], v[162:165], v[124:127]
	v_mfma_f32_16x16x32_bf16 v[120:123], v[154:157], v[162:165], v[120:123]
	v_mfma_f32_16x16x32_bf16 v[116:119], v[146:149], v[170:173], v[116:119]
	v_mfma_f32_16x16x32_bf16 v[112:115], v[154:157], v[170:173], v[112:115]
	v_mfma_f32_16x16x32_bf16 v[100:103], v[146:149], v[182:185], v[100:103]
	v_mfma_f32_16x16x32_bf16 v[96:99], v[154:157], v[182:185], v[96:99]
	v_mfma_f32_16x16x32_bf16 v[84:87], v[146:149], v[190:193], v[84:87]
	v_mfma_f32_16x16x32_bf16 v[80:83], v[154:157], v[190:193], v[80:83]
	s_barrier
	s_add_i32 s47, 0, 0x14000
	v_add_u32_e32 v174, 0x14000, v139
	ds_read_b128 v[194:197], v174
	ds_read_b128 v[198:201], v174 offset:1024
	s_add_u32 s98, s12, 0x80
	s_addc_u32 s99, s13, 0
	s_add_i32 m0, s18, 0x10000
	ds_read_b128 v[202:205], v174 offset:2048
	global_load_lds_dwordx4 v176, s[12:13]
	s_add_i32 m0, s18, 0x12000
	ds_read_b128 v[206:209], v174 offset:3072
	global_load_lds_dwordx4 v128, s[12:13]
	s_barrier
	s_waitcnt lgkmcnt(0)
	v_mfma_f32_16x16x32_bf16 v[108:111], v[194:197], v[158:161], v[108:111]
	v_mfma_f32_16x16x32_bf16 v[104:107], v[202:205], v[158:161], v[104:107]
	v_mfma_f32_16x16x32_bf16 v[92:95], v[194:197], v[166:169], v[92:95]
	v_mfma_f32_16x16x32_bf16 v[88:91], v[202:205], v[166:169], v[88:91]
	v_mfma_f32_16x16x32_bf16 v[76:79], v[194:197], v[178:181], v[76:79]
	v_mfma_f32_16x16x32_bf16 v[72:75], v[202:205], v[178:181], v[72:75]
	v_mfma_f32_16x16x32_bf16 v[68:71], v[194:197], v[186:189], v[68:71]
	v_mfma_f32_16x16x32_bf16 v[64:67], v[202:205], v[186:189], v[64:67]
	v_mfma_f32_16x16x32_bf16 v[108:111], v[198:201], v[162:165], v[108:111]
	v_mfma_f32_16x16x32_bf16 v[104:107], v[206:209], v[162:165], v[104:107]
	v_mfma_f32_16x16x32_bf16 v[92:95], v[198:201], v[170:173], v[92:95]
	v_mfma_f32_16x16x32_bf16 v[88:91], v[206:209], v[170:173], v[88:91]
	v_mfma_f32_16x16x32_bf16 v[76:79], v[198:201], v[182:185], v[76:79]
	v_mfma_f32_16x16x32_bf16 v[72:75], v[206:209], v[182:185], v[72:75]
	v_mfma_f32_16x16x32_bf16 v[68:71], v[198:201], v[190:193], v[68:71]
	v_mfma_f32_16x16x32_bf16 v[64:67], v[206:209], v[190:193], v[64:67]
	s_mov_b32 m0, s20
	s_add_u32 s100, s14, 0x80
	s_addc_u32 s101, s15, 0
	s_barrier
	ds_read_b128 v[158:161], v141 offset:16384
	ds_read_b128 v[162:165], v141 offset:17408
	ds_read_b128 v[166:169], v141 offset:18432
	ds_read_b128 v[170:173], v141 offset:19456
	ds_read_b128 v[178:181], v141 offset:20480
	ds_read_b128 v[182:185], v141 offset:21504
	ds_read_b128 v[186:189], v141 offset:22528
	global_load_lds_dwordx4 v132, s[14:15]
	s_mov_b32 m0, s21
	ds_read_b128 v[190:193], v141 offset:23552
	global_load_lds_dwordx4 v130, s[14:15]
	s_barrier
	s_waitcnt lgkmcnt(0)
	v_mfma_f32_16x16x32_bf16 v[60:63], v[142:145], v[158:161], v[60:63]
	v_mfma_f32_16x16x32_bf16 v[56:59], v[150:153], v[158:161], v[56:59]
	v_mfma_f32_16x16x32_bf16 v[52:55], v[142:145], v[166:169], v[52:55]
	v_mfma_f32_16x16x32_bf16 v[48:51], v[150:153], v[166:169], v[48:51]
	v_mfma_f32_16x16x32_bf16 v[36:39], v[142:145], v[178:181], v[36:39]
	v_mfma_f32_16x16x32_bf16 v[32:35], v[150:153], v[178:181], v[32:35]
	v_mfma_f32_16x16x32_bf16 v[20:23], v[142:145], v[186:189], v[20:23]
	v_mfma_f32_16x16x32_bf16 v[16:19], v[150:153], v[186:189], v[16:19]
	v_mfma_f32_16x16x32_bf16 v[60:63], v[146:149], v[162:165], v[60:63]
	v_mfma_f32_16x16x32_bf16 v[56:59], v[154:157], v[162:165], v[56:59]
	v_mfma_f32_16x16x32_bf16 v[52:55], v[146:149], v[170:173], v[52:55]
	v_mfma_f32_16x16x32_bf16 v[48:51], v[154:157], v[170:173], v[48:51]
	v_mfma_f32_16x16x32_bf16 v[36:39], v[146:149], v[182:185], v[36:39]
	v_mfma_f32_16x16x32_bf16 v[32:35], v[154:157], v[182:185], v[32:35]
	v_mfma_f32_16x16x32_bf16 v[20:23], v[146:149], v[190:193], v[20:23]
	v_mfma_f32_16x16x32_bf16 v[16:19], v[154:157], v[190:193], v[16:19]
	s_barrier
	s_add_u32 s8, s12, 0xb0000
	s_addc_u32 s9, s13, 0
	s_add_i32 m0, s18, 0x14000
	s_nop 0
	global_load_lds_dwordx4 v176, s[8:9]
	s_add_i32 m0, s18, 0x16000
	s_nop 0
	global_load_lds_dwordx4 v128, s[8:9]
	s_waitcnt vmcnt(6)
	s_barrier
; #define PG8_STAGE(bufoff, gbase, voff) do { _Pragma("unroll") for (int _i = 0; _i < 2; ++_i) \
;         __builtin_amdgcn_global_load_lds((const unsigned*)((const char*)(gbase) + (voff)[_i]), (PG8_LAS unsigned*)(lds + (bufoff) + ldsw + _i * 8192), 16, 0, 0); } while (0)
; #define PG8_LDA(dst, b, h) do { _Pragma("unroll") for (int m = 0; m < 4; ++m) _Pragma("unroll") for (int k = 0; k < 2; ++k) dst[m][k] = *(const PG8_LAS bf16x8*)(lds + PG8_SA(b, h) + aoff + m * 2048 + k * 1024); } while (0)
; #define PG8_LDB(dst, b, h) do { _Pragma("unroll") for (int n = 0; n < 2; ++n) _Pragma("unroll") for (int k = 0; k < 2; ++k) dst[n][k] = *(const PG8_LAS bf16x8*)(lds + PG8_SB(b, h) + boff + n * 2048 + k * 1024); } while (0)
; #define PG8_MMA(ai, bj, At, Bt) do { __builtin_amdgcn_s_setprio(1); _Pragma("unroll") for (int m = 0; m < 4; ++m) _Pragma("unroll") for (int n = 0; n < 2; ++n) _Pragma("unroll") for (int k = 0; k < 2; ++k) \
;         acc[ai][bj][m][n] = __builtin_amdgcn_mfma_f32_16x16x32_bf16(Bt[n][k], At[m][k], acc[ai][bj][m][n], 0, 0, 0); __builtin_amdgcn_s_setprio(0); } while (0)
; #define PG8_WAIT_V(n) asm volatile("s_waitcnt vmcnt(" #n ")" ::: "memory")
; #define PG8_WAIT_L(n) asm volatile("s_waitcnt lgkmcnt(" #n ")" ::: "memory")
; #define PG8_BAR __builtin_amdgcn_s_barrier()
; #define PG8_SCHED __builtin_amdgcn_sched_barrier(0)
; template <class Epi, class Sched>
; __device__ __forceinline__ void gemm_phase(PG8_LAS unsigned char* lds, const Gemm g, const Sched& S, const Epi& E) {
;     ...
;             PG8_WAIT_V(6); PG8_BAR; PG8_MMA(1, 1, At, B1); PG8_BAR;
;             PG8_LDB(B0, 1, 0); PG8_SCHED; PG8_LDA(At, 1, 0); PG8_STAGE(PG8_SA(0, 1), a2 + hstep, voffA);
;             PG8_WAIT_L(8); PG8_BAR; PG8_WAIT_L(0); PG8_MMA(0, 0, At, B0); PG8_BAR; PG8_SCHED;
;             PG8_LDB(B1, 1, 1); PG8_STAGE(PG8_SB(1, 0), b3, voffB);
;             PG8_BAR; PG8_WAIT_L(0); PG8_MMA(0, 1, At, B1); PG8_BAR;
;             PG8_LDA(At, 1, 1); PG8_STAGE(PG8_SA(1, 0), a3, voffA);
;             PG8_BAR; PG8_WAIT_L(0); PG8_MMA(1, 0, At, B0); PG8_BAR; PG8_SCHED;
	v_mfma_f32_16x16x32_bf16 v[44:47], v[194:197], v[158:161], v[44:47]
	v_mfma_f32_16x16x32_bf16 v[40:43], v[202:205], v[158:161], v[40:43]
	v_mfma_f32_16x16x32_bf16 v[28:31], v[194:197], v[166:169], v[28:31]
	v_mfma_f32_16x16x32_bf16 v[24:27], v[202:205], v[166:169], v[24:27]
	v_mfma_f32_16x16x32_bf16 v[12:15], v[194:197], v[178:181], v[12:15]
	v_mfma_f32_16x16x32_bf16 v[8:11], v[202:205], v[178:181], v[8:11]
	v_mfma_f32_16x16x32_bf16 v[4:7], v[194:197], v[186:189], v[4:7]
	v_mfma_f32_16x16x32_bf16 v[0:3], v[202:205], v[186:189], v[0:3]
	v_mfma_f32_16x16x32_bf16 v[44:47], v[198:201], v[162:165], v[44:47]
	v_mfma_f32_16x16x32_bf16 v[40:43], v[206:209], v[162:165], v[40:43]
	v_mfma_f32_16x16x32_bf16 v[28:31], v[198:201], v[170:173], v[28:31]
	v_mfma_f32_16x16x32_bf16 v[24:27], v[206:209], v[170:173], v[24:27]
	v_mfma_f32_16x16x32_bf16 v[12:15], v[198:201], v[182:185], v[12:15]
	v_mfma_f32_16x16x32_bf16 v[8:11], v[206:209], v[182:185], v[8:11]
	v_mfma_f32_16x16x32_bf16 v[4:7], v[198:201], v[190:193], v[4:7]
	v_mfma_f32_16x16x32_bf16 v[0:3], v[206:209], v[190:193], v[0:3]
	s_add_i32 s46, 0, 0x18000
	v_add_u32_e32 v154, 0x18000, v139
	s_barrier
	ds_read_b128 v[142:145], v154
	ds_read_b128 v[146:149], v154 offset:1024
	ds_read_b128 v[150:153], v154 offset:2048
	ds_read_b128 v[154:157], v154 offset:3072
	s_add_u32 s8, s14, 0xb0000
	s_addc_u32 s9, s15, 0
	s_mov_b32 m0, s22
	ds_read_b128 v[158:161], v141 offset:32768
	ds_read_b128 v[162:165], v141 offset:33792
	ds_read_b128 v[166:169], v141 offset:34816
	ds_read_b128 v[170:173], v141 offset:35840
	ds_read_b128 v[178:181], v141 offset:36864
	ds_read_b128 v[182:185], v141 offset:37888
	ds_read_b128 v[186:189], v141 offset:38912
	global_load_lds_dwordx4 v132, s[8:9]
	s_mov_b32 m0, s23
	ds_read_b128 v[190:193], v141 offset:39936
	global_load_lds_dwordx4 v130, s[8:9]
	s_waitcnt lgkmcnt(8)
	s_barrier
	s_waitcnt lgkmcnt(0)
	v_mfma_f32_16x16x32_bf16 v[124:127], v[142:145], v[158:161], v[124:127]
	v_mfma_f32_16x16x32_bf16 v[120:123], v[150:153], v[158:161], v[120:123]
	v_mfma_f32_16x16x32_bf16 v[116:119], v[142:145], v[166:169], v[116:119]
	v_mfma_f32_16x16x32_bf16 v[112:115], v[150:153], v[166:169], v[112:115]
	v_mfma_f32_16x16x32_bf16 v[100:103], v[142:145], v[178:181], v[100:103]
	v_mfma_f32_16x16x32_bf16 v[96:99], v[150:153], v[178:181], v[96:99]
	v_mfma_f32_16x16x32_bf16 v[84:87], v[142:145], v[186:189], v[84:87]
	v_mfma_f32_16x16x32_bf16 v[80:83], v[150:153], v[186:189], v[80:83]
	v_mfma_f32_16x16x32_bf16 v[124:127], v[146:149], v[162:165], v[124:127]
	v_mfma_f32_16x16x32_bf16 v[120:123], v[154:157], v[162:165], v[120:123]
	v_mfma_f32_16x16x32_bf16 v[116:119], v[146:149], v[170:173], v[116:119]
	v_mfma_f32_16x16x32_bf16 v[112:115], v[154:157], v[170:173], v[112:115]
	v_mfma_f32_16x16x32_bf16 v[100:103], v[146:149], v[182:185], v[100:103]
	v_mfma_f32_16x16x32_bf16 v[96:99], v[154:157], v[182:185], v[96:99]
	v_mfma_f32_16x16x32_bf16 v[84:87], v[146:149], v[190:193], v[84:87]
	v_mfma_f32_16x16x32_bf16 v[80:83], v[154:157], v[190:193], v[80:83]
	s_barrier
	v_add_u32_e32 v206, 0x1c000, v139
	s_add_i32 m0, s18, 0x18000
	ds_read_b128 v[194:197], v206
	ds_read_b128 v[198:201], v206 offset:1024
	ds_read_b128 v[202:205], v206 offset:2048
	global_load_lds_dwordx4 v176, s[98:99]
	s_add_i32 m0, s18, 0x1a000
	ds_read_b128 v[206:209], v206 offset:3072
	global_load_lds_dwordx4 v128, s[98:99]
	s_barrier
	s_waitcnt lgkmcnt(0)
	v_mfma_f32_16x16x32_bf16 v[108:111], v[194:197], v[158:161], v[108:111]
	v_mfma_f32_16x16x32_bf16 v[104:107], v[202:205], v[158:161], v[104:107]
	v_mfma_f32_16x16x32_bf16 v[92:95], v[194:197], v[166:169], v[92:95]
	v_mfma_f32_16x16x32_bf16 v[88:91], v[202:205], v[166:169], v[88:91]
	v_mfma_f32_16x16x32_bf16 v[76:79], v[194:197], v[178:181], v[76:79]
	v_mfma_f32_16x16x32_bf16 v[72:75], v[202:205], v[178:181], v[72:75]
	v_mfma_f32_16x16x32_bf16 v[68:71], v[194:197], v[186:189], v[68:71]
	v_mfma_f32_16x16x32_bf16 v[64:67], v[202:205], v[186:189], v[64:67]
	v_mfma_f32_16x16x32_bf16 v[108:111], v[198:201], v[162:165], v[108:111]
	v_mfma_f32_16x16x32_bf16 v[104:107], v[206:209], v[162:165], v[104:107]
	v_mfma_f32_16x16x32_bf16 v[92:95], v[198:201], v[170:173], v[92:95]
	v_mfma_f32_16x16x32_bf16 v[88:91], v[206:209], v[170:173], v[88:91]
	v_mfma_f32_16x16x32_bf16 v[76:79], v[198:201], v[182:185], v[76:79]
	v_mfma_f32_16x16x32_bf16 v[72:75], v[206:209], v[182:185], v[72:75]
	v_mfma_f32_16x16x32_bf16 v[68:71], v[198:201], v[190:193], v[68:71]
	v_mfma_f32_16x16x32_bf16 v[64:67], v[206:209], v[190:193], v[64:67]
	s_mov_b32 m0, s27
	s_barrier
	ds_read_b128 v[158:161], v141 offset:49152
	ds_read_b128 v[162:165], v141 offset:50176
	ds_read_b128 v[166:169], v141 offset:51200
	ds_read_b128 v[170:173], v141 offset:52224
	ds_read_b128 v[178:181], v141 offset:53248
	ds_read_b128 v[182:185], v141 offset:54272
	ds_read_b128 v[186:189], v141 offset:55296
	global_load_lds_dwordx4 v132, s[100:101]
	s_mov_b32 m0, s28
	ds_read_b128 v[190:193], v141 offset:56320
	global_load_lds_dwordx4 v130, s[100:101]
	s_barrier
	s_waitcnt lgkmcnt(0)
	v_mfma_f32_16x16x32_bf16 v[60:63], v[142:145], v[158:161], v[60:63]
	v_mfma_f32_16x16x32_bf16 v[56:59], v[150:153], v[158:161], v[56:59]
	v_mfma_f32_16x16x32_bf16 v[52:55], v[142:145], v[166:169], v[52:55]
	v_mfma_f32_16x16x32_bf16 v[48:51], v[150:153], v[166:169], v[48:51]
	v_mfma_f32_16x16x32_bf16 v[36:39], v[142:145], v[178:181], v[36:39]
	v_mfma_f32_16x16x32_bf16 v[32:35], v[150:153], v[178:181], v[32:35]
	v_mfma_f32_16x16x32_bf16 v[20:23], v[142:145], v[186:189], v[20:23]
	v_mfma_f32_16x16x32_bf16 v[16:19], v[150:153], v[186:189], v[16:19]
	v_mfma_f32_16x16x32_bf16 v[60:63], v[146:149], v[162:165], v[60:63]
	v_mfma_f32_16x16x32_bf16 v[56:59], v[154:157], v[162:165], v[56:59]
	v_mfma_f32_16x16x32_bf16 v[52:55], v[146:149], v[170:173], v[52:55]
	v_mfma_f32_16x16x32_bf16 v[48:51], v[154:157], v[170:173], v[48:51]
	v_mfma_f32_16x16x32_bf16 v[36:39], v[146:149], v[182:185], v[36:39]
	v_mfma_f32_16x16x32_bf16 v[32:35], v[154:157], v[182:185], v[32:35]
	v_mfma_f32_16x16x32_bf16 v[20:23], v[146:149], v[190:193], v[20:23]
	v_mfma_f32_16x16x32_bf16 v[16:19], v[154:157], v[190:193], v[16:19]
	s_barrier
; __device__ __forceinline__ unsigned cvtpk(float lo, float hi) { const f32x2 v = (f32x2){lo, hi}; const bf16v2 b = __builtin_convertvector(v, bf16v2); return __builtin_bit_cast(unsigned, b); }
; #define PG8_STAGE(bufoff, gbase, voff) do { _Pragma("unroll") for (int _i = 0; _i < 2; ++_i) \
;         __builtin_amdgcn_global_load_lds((const unsigned*)((const char*)(gbase) + (voff)[_i]), (PG8_LAS unsigned*)(lds + (bufoff) + ldsw + _i * 8192), 16, 0, 0); } while (0)
; #define PG8_MMA(ai, bj, At, Bt) do { __builtin_amdgcn_s_setprio(1); _Pragma("unroll") for (int m = 0; m < 4; ++m) _Pragma("unroll") for (int n = 0; n < 2; ++n) _Pragma("unroll") for (int k = 0; k < 2; ++k) \
;         acc[ai][bj][m][n] = __builtin_amdgcn_mfma_f32_16x16x32_bf16(Bt[n][k], At[m][k], acc[ai][bj][m][n], 0, 0, 0); __builtin_amdgcn_s_setprio(0); } while (0)
; #define PG8_WAIT_V(n) asm volatile("s_waitcnt vmcnt(" #n ")" ::: "memory")
; #define PG8_BAR __builtin_amdgcn_s_barrier()
; template <class Epi, class Sched>
; __device__ __forceinline__ void gemm_phase(PG8_LAS unsigned char* lds, const Gemm g, const Sched& S, const Epi& E) {
;     ...
;             PG8_STAGE(PG8_SB(1, 1), b3 + hstep, voffB);
;             PG8_WAIT_V(6); PG8_BAR; PG8_MMA(1, 1, At, B1); PG8_BAR;
;         }
;         if constexpr (!Epi::AFTER_DRAIN) { E(acc, cur, wr, wc, fr, fq); S.done(cur); }
;     __device__ __forceinline__ void operator()(const f32x4 (&acc)[2][2][4][2], const pg8::Unit& u, int wr, int wc, int fr, int fq) const {
;         const int row0 = u.pm * 256 + wr * 64 + fr, col0 = u.pn * 256 + wc * 32 + 8 * fq;
; #pragma unroll
;         for (int ai = 0; ai < 2; ++ai)
; #pragma unroll
;             for (int m = 0; m < 4; ++m) { bf16_t* rowp = O + (size_t)(row0 + ai * 128 + m * 16) * ldc + col0;
; #pragma unroll
;                 for (int bj = 0; bj < 2; ++bj) { const f32x4 v0 = acc[ai][bj][m][0], v1 = acc[ai][bj][m][1];
;                     u32x4 w; w.x = cvtpk(v0[0], v0[1]); w.y = cvtpk(v0[2], v0[3]); w.z = cvtpk(v1[0], v1[1]); w.w = cvtpk(v1[2], v1[3]);
;                     *(u32x4*)(rowp + bj * 128) = w; } }
	s_add_u32 s8, s12, 0xb0080
	s_addc_u32 s9, s13, 0
	s_add_i32 m0, s18, 0x1c000
	s_nop 0
	global_load_lds_dwordx4 v176, s[8:9]
	s_add_i32 m0, s18, 0x1e000
	s_nop 0
	global_load_lds_dwordx4 v128, s[8:9]
	s_waitcnt vmcnt(6)
	s_barrier
	v_mfma_f32_16x16x32_bf16 v[44:47], v[194:197], v[158:161], v[44:47]
	v_mfma_f32_16x16x32_bf16 v[40:43], v[202:205], v[158:161], v[40:43]
	v_mfma_f32_16x16x32_bf16 v[28:31], v[194:197], v[166:169], v[28:31]
	v_mfma_f32_16x16x32_bf16 v[24:27], v[202:205], v[166:169], v[24:27]
	v_mfma_f32_16x16x32_bf16 v[12:15], v[194:197], v[178:181], v[12:15]
	v_mfma_f32_16x16x32_bf16 v[8:11], v[202:205], v[178:181], v[8:11]
	v_mfma_f32_16x16x32_bf16 v[4:7], v[194:197], v[186:189], v[4:7]
	v_mfma_f32_16x16x32_bf16 v[0:3], v[202:205], v[186:189], v[0:3]
	v_mfma_f32_16x16x32_bf16 v[44:47], v[198:201], v[162:165], v[44:47]
	v_mfma_f32_16x16x32_bf16 v[40:43], v[206:209], v[162:165], v[40:43]
	v_mfma_f32_16x16x32_bf16 v[28:31], v[198:201], v[170:173], v[28:31]
	v_mfma_f32_16x16x32_bf16 v[24:27], v[206:209], v[170:173], v[24:27]
	v_mfma_f32_16x16x32_bf16 v[12:15], v[198:201], v[182:185], v[12:15]
	v_mfma_f32_16x16x32_bf16 v[8:11], v[206:209], v[182:185], v[8:11]
	v_mfma_f32_16x16x32_bf16 v[4:7], v[198:201], v[190:193], v[4:7]
	v_mfma_f32_16x16x32_bf16 v[0:3], v[206:209], v[190:193], v[0:3]
	s_add_i32 s45, s45, 2
	s_add_u32 s43, s43, 0x100
	s_addc_u32 s44, s44, 0
	s_cmp_gt_u32 s45, 41
	s_mov_b64 s[8:9], s[10:11]
	s_barrier
	s_cbranch_scc0 .LBB0_96
	v_lshl_add_u32 v142, s29, 8, v138
	v_lshl_or_b32 v144, s34, 8, v140
	v_ashrrev_i32_e32 v143, 31, v142
	v_readlane_b32 s8, v253, 18
	v_cvt_pk_bf16_f32 v108, v108, v109
	v_cvt_pk_bf16_f32 v109, v110, v111
	v_cvt_pk_bf16_f32 v110, v104, v105
	v_or_b32_e32 v104, 16, v142
	v_cvt_pk_bf16_f32 v92, v92, v93
	v_cvt_pk_bf16_f32 v93, v94, v95
	v_cvt_pk_bf16_f32 v94, v88, v89
	v_or_b32_e32 v88, 32, v142
	v_cvt_pk_bf16_f32 v76, v76, v77
	v_cvt_pk_bf16_f32 v77, v78, v79
	v_cvt_pk_bf16_f32 v78, v72, v73
	v_or_b32_e32 v72, 48, v142
	v_ashrrev_i32_e32 v145, 31, v144
	v_lshlrev_b64 v[146:147], 11, v[142:143]
	v_readlane_b32 s9, v253, 19
	v_ashrrev_i32_e32 v105, 31, v104
	v_ashrrev_i32_e32 v89, 31, v88
	v_ashrrev_i32_e32 v73, 31, v72
	v_lshl_add_u64 v[146:147], s[8:9], 0, v[146:147]
	v_lshlrev_b64 v[144:145], 1, v[144:145]
	v_lshlrev_b64 v[104:105], 11, v[104:105]
	v_lshlrev_b64 v[88:89], 11, v[88:89]
	v_lshlrev_b64 v[72:73], 11, v[72:73]
	v_lshl_add_u64 v[146:147], v[146:147], 0, v[144:145]
	v_lshl_add_u64 v[104:105], s[8:9], 0, v[104:105]
	v_lshl_add_u64 v[88:89], s[8:9], 0, v[88:89]
	v_lshl_add_u64 v[72:73], s[8:9], 0, v[72:73]
	s_mov_b64 s[8:9], 0x40000
	v_cvt_pk_bf16_f32 v68, v68, v69
	v_cvt_pk_bf16_f32 v69, v70, v71
	v_cvt_pk_bf16_f32 v70, v64, v65
	v_lshl_add_u64 v[64:65], v[146:147], 0, s[8:9]
	v_cvt_pk_bf16_f32 v60, v60, v61
	v_cvt_pk_bf16_f32 v61, v62, v63
	v_cvt_pk_bf16_f32 v62, v56, v57
	v_add_co_u32_e32 v56, vcc, s2, v146
	v_cvt_pk_bf16_f32 v44, v44, v45
	v_cvt_pk_bf16_f32 v45, v46, v47
	v_cvt_pk_bf16_f32 v46, v40, v41
	v_cvt_pk_bf16_f32 v47, v42, v43
	s_mov_b64 s[8:9], 0x48000
	v_addc_co_u32_e32 v57, vcc, 0, v147, vcc
	global_store_dwordx4 v[64:65], v[44:47], off offset:256
	v_cvt_pk_bf16_f32 v28, v28, v29
	v_cvt_pk_bf16_f32 v29, v30, v31
	v_lshl_add_u64 v[44:45], v[146:147], 0, s[8:9]
	s_mov_b32 s8, 0x48000
	v_add_co_u32_e32 v46, vcc, s8, v146
	v_cvt_pk_bf16_f32 v30, v24, v25
	v_cvt_pk_bf16_f32 v31, v26, v27
	s_mov_b64 s[8:9], 0x50000
	v_addc_co_u32_e32 v47, vcc, 0, v147, vcc
	global_store_dwordx4 v[44:45], v[28:31], off offset:256
	v_cvt_pk_bf16_f32 v12, v12, v13
	v_cvt_pk_bf16_f32 v13, v14, v15
	v_lshl_add_u64 v[28:29], v[146:147], 0, s[8:9]
	s_mov_b32 s8, 0x50000
	v_add_co_u32_e32 v30, vcc, s8, v146
	v_cvt_pk_bf16_f32 v14, v8, v9
	v_cvt_pk_bf16_f32 v15, v10, v11
	s_mov_b64 s[8:9], 0x58000
	v_cvt_pk_bf16_f32 v111, v106, v107
	v_addc_co_u32_e32 v31, vcc, 0, v147, vcc
	global_store_dwordx4 v[28:29], v[12:15], off offset:256
	global_store_dwordx4 v[146:147], v[108:111], off offset:256
	v_cvt_pk_bf16_f32 v95, v90, v91
	v_lshl_add_u64 v[12:13], v[146:147], 0, s[8:9]
	s_mov_b32 s8, 0x58000
	v_lshl_add_u64 v[108:109], v[104:105], 0, v[144:145]
	v_add_co_u32_e32 v14, vcc, s8, v146
	global_store_dwordx4 v[108:109], v[92:95], off offset:256
	v_cvt_pk_bf16_f32 v79, v74, v75
	v_addc_co_u32_e32 v15, vcc, 0, v147, vcc
	v_lshl_add_u64 v[92:93], v[88:89], 0, v[144:145]
	v_cvt_pk_bf16_f32 v124, v124, v125
	v_cvt_pk_bf16_f32 v125, v126, v127
	v_cvt_pk_bf16_f32 v126, v120, v121
	v_cvt_pk_bf16_f32 v127, v122, v123
	v_cvt_pk_bf16_f32 v104, v116, v117
	v_cvt_pk_bf16_f32 v105, v118, v119
	v_cvt_pk_bf16_f32 v106, v112, v113
	v_cvt_pk_bf16_f32 v107, v114, v115
	v_cvt_pk_bf16_f32 v88, v100, v101
	v_cvt_pk_bf16_f32 v89, v102, v103
	v_cvt_pk_bf16_f32 v90, v96, v97
	v_cvt_pk_bf16_f32 v91, v98, v99
	global_store_dwordx4 v[92:93], v[76:79], off offset:256
	v_cvt_pk_bf16_f32 v74, v80, v81
	v_cvt_pk_bf16_f32 v75, v82, v83
	v_lshl_add_u64 v[76:77], v[72:73], 0, v[144:145]
	v_cvt_pk_bf16_f32 v72, v84, v85
	v_cvt_pk_bf16_f32 v73, v86, v87
	v_cvt_pk_bf16_f32 v71, v66, v67
	v_cvt_pk_bf16_f32 v63, v58, v59
	v_cvt_pk_bf16_f32 v40, v52, v53
	v_cvt_pk_bf16_f32 v41, v54, v55
	v_cvt_pk_bf16_f32 v42, v48, v49
	v_cvt_pk_bf16_f32 v43, v50, v51
	v_cvt_pk_bf16_f32 v24, v36, v37
	v_cvt_pk_bf16_f32 v25, v38, v39
	v_cvt_pk_bf16_f32 v26, v32, v33
	v_cvt_pk_bf16_f32 v27, v34, v35
	v_cvt_pk_bf16_f32 v8, v20, v21
	v_cvt_pk_bf16_f32 v9, v22, v23
	v_cvt_pk_bf16_f32 v10, v16, v17
	v_cvt_pk_bf16_f32 v11, v18, v19
	v_cvt_pk_bf16_f32 v4, v4, v5
	v_cvt_pk_bf16_f32 v5, v6, v7
	v_cvt_pk_bf16_f32 v6, v0, v1
	v_cvt_pk_bf16_f32 v7, v2, v3
	s_and_b64 vcc, exec, s[38:39]
	s_mov_b32 s34, s40
	s_mov_b32 s29, s41
	s_mov_b64 s[10:11], s[4:5]
	s_mov_b64 s[8:9], s[0:1]
	global_store_dwordx4 v[146:147], v[124:127], off
	global_store_dwordx4 v[108:109], v[104:107], off
	global_store_dwordx4 v[92:93], v[88:91], off
	global_store_dwordx4 v[76:77], v[72:75], off
	global_store_dwordx4 v[76:77], v[68:71], off offset:256
	global_store_dwordx4 v[56:57], v[60:63], off
	global_store_dwordx4 v[46:47], v[40:43], off
	global_store_dwordx4 v[30:31], v[24:27], off
	global_store_dwordx4 v[14:15], v[8:11], off
	global_store_dwordx4 v[12:13], v[4:7], off offset:256
	s_cbranch_vccz .LBB0_89
	s_waitcnt vmcnt(0)
	s_cmpk_gt_u32 s17, 0xff
	v_readlane_b32 s2, v254, 59
	s_cbranch_scc1 .LBB0_100
	s_barrier

; #define PG8_STAGE(bufoff, gbase, voff) do { _Pragma("unroll") for (int _i = 0; _i < 2; ++_i) \
;         __builtin_amdgcn_global_load_lds((const unsigned*)((const char*)(gbase) + (voff)[_i]), (PG8_LAS unsigned*)(lds + (bufoff) + ldsw + _i * 8192), 16, 0, 0); } while (0)
; #define PG8_LDA(dst, b, h) do { _Pragma("unroll") for (int m = 0; m < 4; ++m) _Pragma("unroll") for (int k = 0; k < 2; ++k) dst[m][k] = *(const PG8_LAS bf16x8*)(lds + PG8_SA(b, h) + aoff + m * 2048 + k * 1024); } while (0)
; #define PG8_LDB(dst, b, h) do { _Pragma("unroll") for (int n = 0; n < 2; ++n) _Pragma("unroll") for (int k = 0; k < 2; ++k) dst[n][k] = *(const PG8_LAS bf16x8*)(lds + PG8_SB(b, h) + boff + n * 2048 + k * 1024); } while (0)
; #define PG8_MMA(ai, bj, At, Bt) do { __builtin_amdgcn_s_setprio(1); _Pragma("unroll") for (int m = 0; m < 4; ++m) _Pragma("unroll") for (int n = 0; n < 2; ++n) _Pragma("unroll") for (int k = 0; k < 2; ++k) \
;         acc[ai][bj][m][n] = __builtin_amdgcn_mfma_f32_16x16x32_bf16(Bt[n][k], At[m][k], acc[ai][bj][m][n], 0, 0, 0); __builtin_amdgcn_s_setprio(0); } while (0)
; #define PG8_WAIT_V(n) asm volatile("s_waitcnt vmcnt(" #n ")" ::: "memory")
; template <class Epi, class Sched>
; __device__ __forceinline__ void gemm_phase(PG8_LAS unsigned char* lds, const Gemm g, const Sched& S, const Epi& E) {
;     ...
;         for (int t = 0; t < nt; t += 2) {
;             const bool last = (t == nt - 2);
;             const char* a1 = cA + (size_t)(t + 1) * kstep;
;             const char* a2 = last ? nA : cA + (size_t)(t + 2) * kstep; const char* b2 = last ? nB : cB + (size_t)(t + 2) * kstep;
;             const char* a3 = a2 + kstep; const char* b3 = b2 + kstep;
;             if (last && has_next) S.a_ready(nxt);
;             PG8_LDB(B0, 0, 0); PG8_SCHED; PG8_LDA(At, 0, 0); PG8_STAGE(PG8_SA(1, 1), a1 + hstep, voffA);
;             PG8_WAIT_L(8); PG8_BAR; PG8_WAIT_L(0); PG8_MMA(0, 0, At, B0); PG8_BAR; PG8_SCHED;
;             PG8_LDB(B1, 0, 1); PG8_STAGE(PG8_SB(0, 0), b2, voffB);
;             PG8_BAR; PG8_WAIT_L(0); PG8_MMA(0, 1, At, B1); PG8_BAR;
;             PG8_LDA(At, 0, 1); PG8_STAGE(PG8_SA(0, 0), a2, voffA);
;             PG8_BAR; PG8_WAIT_L(0); PG8_MMA(1, 0, At, B0); PG8_BAR; PG8_SCHED;
;             PG8_STAGE(PG8_SB(0, 1), b2 + hstep, voffB);
;             PG8_WAIT_V(6); PG8_BAR; PG8_MMA(1, 1, At, B1); PG8_BAR;
.LBB0_114:
	s_add_u32 s14, s12, 0xfffc0080
	s_addc_u32 s15, s13, -1
	v_add_u32_e32 v154, 0x10000, v143
	ds_read_b128 v[138:141], v154
	ds_read_b128 v[146:149], v154 offset:1024
	ds_read_b128 v[150:153], v154 offset:2048
	ds_read_b128 v[154:157], v154 offset:3072
	s_cmp_eq_u32 s45, 12
	s_cselect_b32 s17, s5, s15
	s_cselect_b32 s16, s40, s14
	s_cselect_b32 s15, s1, s44
	s_cselect_b32 s14, s41, s43
	s_add_i32 m0, s11, 0xc000
	ds_read_b128 v[158:161], v145
	ds_read_b128 v[162:165], v145 offset:1024
	ds_read_b128 v[166:169], v145 offset:2048
	ds_read_b128 v[170:173], v145 offset:3072
	ds_read_b128 v[178:181], v145 offset:4096
	ds_read_b128 v[182:185], v145 offset:5120
	ds_read_b128 v[186:189], v145 offset:6144
	global_load_lds_dwordx4 v134, s[12:13]
	s_add_i32 m0, s11, 0xe000
	ds_read_b128 v[190:193], v145 offset:7168
	global_load_lds_dwordx4 v136, s[12:13]
	s_waitcnt lgkmcnt(8)
	s_barrier
	s_waitcnt lgkmcnt(0)
	v_mfma_f32_16x16x32_bf16 v[124:127], v[138:141], v[158:161], v[124:127]
	v_mfma_f32_16x16x32_bf16 v[116:119], v[150:153], v[158:161], v[116:119]
	v_mfma_f32_16x16x32_bf16 v[108:111], v[138:141], v[166:169], v[108:111]
	v_mfma_f32_16x16x32_bf16 v[100:103], v[150:153], v[166:169], v[100:103]
	v_mfma_f32_16x16x32_bf16 v[92:95], v[138:141], v[178:181], v[92:95]
	v_mfma_f32_16x16x32_bf16 v[84:87], v[150:153], v[178:181], v[84:87]
	v_mfma_f32_16x16x32_bf16 v[76:79], v[138:141], v[186:189], v[76:79]
	v_mfma_f32_16x16x32_bf16 v[68:71], v[150:153], v[186:189], v[68:71]
	v_mfma_f32_16x16x32_bf16 v[124:127], v[146:149], v[162:165], v[124:127]
	v_mfma_f32_16x16x32_bf16 v[116:119], v[154:157], v[162:165], v[116:119]
	v_mfma_f32_16x16x32_bf16 v[108:111], v[146:149], v[170:173], v[108:111]
	v_mfma_f32_16x16x32_bf16 v[100:103], v[154:157], v[170:173], v[100:103]
	v_mfma_f32_16x16x32_bf16 v[92:95], v[146:149], v[182:185], v[92:95]
	v_mfma_f32_16x16x32_bf16 v[84:87], v[154:157], v[182:185], v[84:87]
	v_mfma_f32_16x16x32_bf16 v[76:79], v[146:149], v[190:193], v[76:79]
	v_mfma_f32_16x16x32_bf16 v[68:71], v[154:157], v[190:193], v[68:71]
	s_barrier
	s_add_i32 s48, 0, 0x14000
	v_add_u32_e32 v174, 0x14000, v143
	ds_read_b128 v[194:197], v174
	ds_read_b128 v[198:201], v174 offset:1024
	s_add_u32 s98, s14, 0x80
	s_addc_u32 s99, s15, 0
	s_add_i32 m0, s20, 0x10000
	ds_read_b128 v[202:205], v174 offset:2048
	global_load_lds_dwordx4 v176, s[14:15]
	s_add_i32 m0, s20, 0x12000
	ds_read_b128 v[206:209], v174 offset:3072
	global_load_lds_dwordx4 v128, s[14:15]
	s_barrier
	s_waitcnt lgkmcnt(0)
	v_mfma_f32_16x16x32_bf16 v[120:123], v[194:197], v[158:161], v[120:123]
	v_mfma_f32_16x16x32_bf16 v[112:115], v[202:205], v[158:161], v[112:115]
	v_mfma_f32_16x16x32_bf16 v[104:107], v[194:197], v[166:169], v[104:107]
	v_mfma_f32_16x16x32_bf16 v[96:99], v[202:205], v[166:169], v[96:99]
	v_mfma_f32_16x16x32_bf16 v[88:91], v[194:197], v[178:181], v[88:91]
	v_mfma_f32_16x16x32_bf16 v[80:83], v[202:205], v[178:181], v[80:83]
	v_mfma_f32_16x16x32_bf16 v[72:75], v[194:197], v[186:189], v[72:75]
	v_mfma_f32_16x16x32_bf16 v[64:67], v[202:205], v[186:189], v[64:67]
	v_mfma_f32_16x16x32_bf16 v[120:123], v[198:201], v[162:165], v[120:123]
	v_mfma_f32_16x16x32_bf16 v[112:115], v[206:209], v[162:165], v[112:115]
	v_mfma_f32_16x16x32_bf16 v[104:107], v[198:201], v[170:173], v[104:107]
	v_mfma_f32_16x16x32_bf16 v[96:99], v[206:209], v[170:173], v[96:99]
	v_mfma_f32_16x16x32_bf16 v[88:91], v[198:201], v[182:185], v[88:91]
	v_mfma_f32_16x16x32_bf16 v[80:83], v[206:209], v[182:185], v[80:83]
	v_mfma_f32_16x16x32_bf16 v[72:75], v[198:201], v[190:193], v[72:75]
	v_mfma_f32_16x16x32_bf16 v[64:67], v[206:209], v[190:193], v[64:67]
	s_mov_b32 m0, s11
	s_add_u32 s100, s16, 0x80
	s_addc_u32 s101, s17, 0
	s_barrier
	ds_read_b128 v[158:161], v145 offset:16384
	ds_read_b128 v[162:165], v145 offset:17408
	ds_read_b128 v[166:169], v145 offset:18432
	ds_read_b128 v[170:173], v145 offset:19456
	ds_read_b128 v[178:181], v145 offset:20480
	ds_read_b128 v[182:185], v145 offset:21504
	ds_read_b128 v[186:189], v145 offset:22528
	global_load_lds_dwordx4 v132, s[16:17]
	s_mov_b32 m0, s22
	ds_read_b128 v[190:193], v145 offset:23552
	global_load_lds_dwordx4 v130, s[16:17]
	s_barrier
	s_waitcnt lgkmcnt(0)
	v_mfma_f32_16x16x32_bf16 v[60:63], v[138:141], v[158:161], v[60:63]
	v_mfma_f32_16x16x32_bf16 v[52:55], v[150:153], v[158:161], v[52:55]
	v_mfma_f32_16x16x32_bf16 v[44:47], v[138:141], v[166:169], v[44:47]
	v_mfma_f32_16x16x32_bf16 v[36:39], v[150:153], v[166:169], v[36:39]
	v_mfma_f32_16x16x32_bf16 v[28:31], v[138:141], v[178:181], v[28:31]
	v_mfma_f32_16x16x32_bf16 v[20:23], v[150:153], v[178:181], v[20:23]
	v_mfma_f32_16x16x32_bf16 v[12:15], v[138:141], v[186:189], v[12:15]
	v_mfma_f32_16x16x32_bf16 v[4:7], v[150:153], v[186:189], v[4:7]
	v_mfma_f32_16x16x32_bf16 v[60:63], v[146:149], v[162:165], v[60:63]
	v_mfma_f32_16x16x32_bf16 v[52:55], v[154:157], v[162:165], v[52:55]
	v_mfma_f32_16x16x32_bf16 v[44:47], v[146:149], v[170:173], v[44:47]
	v_mfma_f32_16x16x32_bf16 v[36:39], v[154:157], v[170:173], v[36:39]
	v_mfma_f32_16x16x32_bf16 v[28:31], v[146:149], v[182:185], v[28:31]
	v_mfma_f32_16x16x32_bf16 v[20:23], v[154:157], v[182:185], v[20:23]
	v_mfma_f32_16x16x32_bf16 v[12:15], v[146:149], v[190:193], v[12:15]
	v_mfma_f32_16x16x32_bf16 v[4:7], v[154:157], v[190:193], v[4:7]
	s_barrier
	s_add_u32 s46, s14, 0x40000
	s_addc_u32 s47, s15, 0
	s_add_i32 m0, s20, 0x14000
	s_nop 0
	global_load_lds_dwordx4 v176, s[46:47]
	s_add_i32 m0, s20, 0x16000
	s_nop 0
	global_load_lds_dwordx4 v128, s[46:47]
	s_waitcnt vmcnt(6)
	s_barrier
; #define PG8_STAGE(bufoff, gbase, voff) do { _Pragma("unroll") for (int _i = 0; _i < 2; ++_i) \
;         __builtin_amdgcn_global_load_lds((const unsigned*)((const char*)(gbase) + (voff)[_i]), (PG8_LAS unsigned*)(lds + (bufoff) + ldsw + _i * 8192), 16, 0, 0); } while (0)
; #define PG8_LDA(dst, b, h) do { _Pragma("unroll") for (int m = 0; m < 4; ++m) _Pragma("unroll") for (int k = 0; k < 2; ++k) dst[m][k] = *(const PG8_LAS bf16x8*)(lds + PG8_SA(b, h) + aoff + m * 2048 + k * 1024); } while (0)
; #define PG8_LDB(dst, b, h) do { _Pragma("unroll") for (int n = 0; n < 2; ++n) _Pragma("unroll") for (int k = 0; k < 2; ++k) dst[n][k] = *(const PG8_LAS bf16x8*)(lds + PG8_SB(b, h) + boff + n * 2048 + k * 1024); } while (0)
; #define PG8_MMA(ai, bj, At, Bt) do { __builtin_amdgcn_s_setprio(1); _Pragma("unroll") for (int m = 0; m < 4; ++m) _Pragma("unroll") for (int n = 0; n < 2; ++n) _Pragma("unroll") for (int k = 0; k < 2; ++k) \
;         acc[ai][bj][m][n] = __builtin_amdgcn_mfma_f32_16x16x32_bf16(Bt[n][k], At[m][k], acc[ai][bj][m][n], 0, 0, 0); __builtin_amdgcn_s_setprio(0); } while (0)
; #define PG8_WAIT_V(n) asm volatile("s_waitcnt vmcnt(" #n ")" ::: "memory")
; #define PG8_WAIT_L(n) asm volatile("s_waitcnt lgkmcnt(" #n ")" ::: "memory")
; #define PG8_BAR __builtin_amdgcn_s_barrier()
; #define PG8_SCHED __builtin_amdgcn_sched_barrier(0)
; template <class Epi, class Sched>
; __device__ __forceinline__ void gemm_phase(PG8_LAS unsigned char* lds, const Gemm g, const Sched& S, const Epi& E) {
;     ...
;             PG8_WAIT_V(6); PG8_BAR; PG8_MMA(1, 1, At, B1); PG8_BAR;
;             PG8_LDB(B0, 1, 0); PG8_SCHED; PG8_LDA(At, 1, 0); PG8_STAGE(PG8_SA(0, 1), a2 + hstep, voffA);
;             PG8_WAIT_L(8); PG8_BAR; PG8_WAIT_L(0); PG8_MMA(0, 0, At, B0); PG8_BAR; PG8_SCHED;
;             PG8_LDB(B1, 1, 1); PG8_STAGE(PG8_SB(1, 0), b3, voffB);
;             PG8_BAR; PG8_WAIT_L(0); PG8_MMA(0, 1, At, B1); PG8_BAR;
;             PG8_LDA(At, 1, 1); PG8_STAGE(PG8_SA(1, 0), a3, voffA);
;             PG8_BAR; PG8_WAIT_L(0); PG8_MMA(1, 0, At, B0); PG8_BAR; PG8_SCHED;
	v_mfma_f32_16x16x32_bf16 v[56:59], v[194:197], v[158:161], v[56:59]
	v_mfma_f32_16x16x32_bf16 v[48:51], v[202:205], v[158:161], v[48:51]
	v_mfma_f32_16x16x32_bf16 v[40:43], v[194:197], v[166:169], v[40:43]
	v_mfma_f32_16x16x32_bf16 v[32:35], v[202:205], v[166:169], v[32:35]
	v_mfma_f32_16x16x32_bf16 v[24:27], v[194:197], v[178:181], v[24:27]
	v_mfma_f32_16x16x32_bf16 v[16:19], v[202:205], v[178:181], v[16:19]
	v_mfma_f32_16x16x32_bf16 v[8:11], v[194:197], v[186:189], v[8:11]
	v_mfma_f32_16x16x32_bf16 v[0:3], v[202:205], v[186:189], v[0:3]
	v_mfma_f32_16x16x32_bf16 v[56:59], v[198:201], v[162:165], v[56:59]
	v_mfma_f32_16x16x32_bf16 v[48:51], v[206:209], v[162:165], v[48:51]
	v_mfma_f32_16x16x32_bf16 v[40:43], v[198:201], v[170:173], v[40:43]
	v_mfma_f32_16x16x32_bf16 v[32:35], v[206:209], v[170:173], v[32:35]
	v_mfma_f32_16x16x32_bf16 v[24:27], v[198:201], v[182:185], v[24:27]
	v_mfma_f32_16x16x32_bf16 v[16:19], v[206:209], v[182:185], v[16:19]
	v_mfma_f32_16x16x32_bf16 v[8:11], v[198:201], v[190:193], v[8:11]
	v_mfma_f32_16x16x32_bf16 v[0:3], v[206:209], v[190:193], v[0:3]
	v_add_u32_e32 v154, 0x18000, v143
	s_barrier
	ds_read_b128 v[138:141], v154
	ds_read_b128 v[146:149], v154 offset:1024
	ds_read_b128 v[150:153], v154 offset:2048
	ds_read_b128 v[154:157], v154 offset:3072
	s_add_u32 s16, s16, 0x40000
	s_addc_u32 s17, s17, 0
	s_mov_b32 m0, s23
	ds_read_b128 v[158:161], v145 offset:32768
	ds_read_b128 v[162:165], v145 offset:33792
	ds_read_b128 v[166:169], v145 offset:34816
	ds_read_b128 v[170:173], v145 offset:35840
	ds_read_b128 v[178:181], v145 offset:36864
	ds_read_b128 v[182:185], v145 offset:37888
	ds_read_b128 v[186:189], v145 offset:38912
	global_load_lds_dwordx4 v132, s[16:17]
	s_mov_b32 m0, s26
	ds_read_b128 v[190:193], v145 offset:39936
	global_load_lds_dwordx4 v130, s[16:17]
	s_waitcnt lgkmcnt(8)
	s_barrier
	s_waitcnt lgkmcnt(0)
	v_mfma_f32_16x16x32_bf16 v[124:127], v[138:141], v[158:161], v[124:127]
	v_mfma_f32_16x16x32_bf16 v[116:119], v[150:153], v[158:161], v[116:119]
	v_mfma_f32_16x16x32_bf16 v[108:111], v[138:141], v[166:169], v[108:111]
	v_mfma_f32_16x16x32_bf16 v[100:103], v[150:153], v[166:169], v[100:103]
	v_mfma_f32_16x16x32_bf16 v[92:95], v[138:141], v[178:181], v[92:95]
	v_mfma_f32_16x16x32_bf16 v[84:87], v[150:153], v[178:181], v[84:87]
	v_mfma_f32_16x16x32_bf16 v[76:79], v[138:141], v[186:189], v[76:79]
	v_mfma_f32_16x16x32_bf16 v[68:71], v[150:153], v[186:189], v[68:71]
	v_mfma_f32_16x16x32_bf16 v[124:127], v[146:149], v[162:165], v[124:127]
	v_mfma_f32_16x16x32_bf16 v[116:119], v[154:157], v[162:165], v[116:119]
	v_mfma_f32_16x16x32_bf16 v[108:111], v[146:149], v[170:173], v[108:111]
	v_mfma_f32_16x16x32_bf16 v[100:103], v[154:157], v[170:173], v[100:103]
	v_mfma_f32_16x16x32_bf16 v[92:95], v[146:149], v[182:185], v[92:95]
	v_mfma_f32_16x16x32_bf16 v[84:87], v[154:157], v[182:185], v[84:87]
	v_mfma_f32_16x16x32_bf16 v[76:79], v[146:149], v[190:193], v[76:79]
	v_mfma_f32_16x16x32_bf16 v[68:71], v[154:157], v[190:193], v[68:71]
	s_barrier
	v_add_u32_e32 v206, 0x1c000, v143
	s_add_i32 m0, s20, 0x18000
	ds_read_b128 v[194:197], v206
	ds_read_b128 v[198:201], v206 offset:1024
	ds_read_b128 v[202:205], v206 offset:2048
	global_load_lds_dwordx4 v176, s[98:99]
	s_add_i32 m0, s20, 0x1a000
	ds_read_b128 v[206:209], v206 offset:3072
	global_load_lds_dwordx4 v128, s[98:99]
	s_barrier
	s_waitcnt lgkmcnt(0)
	v_mfma_f32_16x16x32_bf16 v[120:123], v[194:197], v[158:161], v[120:123]
	v_mfma_f32_16x16x32_bf16 v[112:115], v[202:205], v[158:161], v[112:115]
	v_mfma_f32_16x16x32_bf16 v[104:107], v[194:197], v[166:169], v[104:107]
	v_mfma_f32_16x16x32_bf16 v[96:99], v[202:205], v[166:169], v[96:99]
	v_mfma_f32_16x16x32_bf16 v[88:91], v[194:197], v[178:181], v[88:91]
	v_mfma_f32_16x16x32_bf16 v[80:83], v[202:205], v[178:181], v[80:83]
	v_mfma_f32_16x16x32_bf16 v[72:75], v[194:197], v[186:189], v[72:75]
	v_mfma_f32_16x16x32_bf16 v[64:67], v[202:205], v[186:189], v[64:67]
	v_mfma_f32_16x16x32_bf16 v[120:123], v[198:201], v[162:165], v[120:123]
	v_mfma_f32_16x16x32_bf16 v[112:115], v[206:209], v[162:165], v[112:115]
	v_mfma_f32_16x16x32_bf16 v[104:107], v[198:201], v[170:173], v[104:107]
	v_mfma_f32_16x16x32_bf16 v[96:99], v[206:209], v[170:173], v[96:99]
	v_mfma_f32_16x16x32_bf16 v[88:91], v[198:201], v[182:185], v[88:91]
	v_mfma_f32_16x16x32_bf16 v[80:83], v[206:209], v[182:185], v[80:83]
	v_mfma_f32_16x16x32_bf16 v[72:75], v[198:201], v[190:193], v[72:75]
	v_mfma_f32_16x16x32_bf16 v[64:67], v[206:209], v[190:193], v[64:67]
	s_mov_b32 m0, s28
	s_barrier
	ds_read_b128 v[158:161], v145 offset:49152
	ds_read_b128 v[162:165], v145 offset:50176
	ds_read_b128 v[166:169], v145 offset:51200
	ds_read_b128 v[170:173], v145 offset:52224
	ds_read_b128 v[178:181], v145 offset:53248
	ds_read_b128 v[182:185], v145 offset:54272
	ds_read_b128 v[186:189], v145 offset:55296
	global_load_lds_dwordx4 v132, s[100:101]
	s_mov_b32 m0, s29
	ds_read_b128 v[190:193], v145 offset:56320
	global_load_lds_dwordx4 v130, s[100:101]
	s_barrier
	s_waitcnt lgkmcnt(0)
	v_mfma_f32_16x16x32_bf16 v[60:63], v[138:141], v[158:161], v[60:63]
	v_mfma_f32_16x16x32_bf16 v[52:55], v[150:153], v[158:161], v[52:55]
	v_mfma_f32_16x16x32_bf16 v[44:47], v[138:141], v[166:169], v[44:47]
	v_mfma_f32_16x16x32_bf16 v[36:39], v[150:153], v[166:169], v[36:39]
	v_mfma_f32_16x16x32_bf16 v[28:31], v[138:141], v[178:181], v[28:31]
	v_mfma_f32_16x16x32_bf16 v[20:23], v[150:153], v[178:181], v[20:23]
	v_mfma_f32_16x16x32_bf16 v[12:15], v[138:141], v[186:189], v[12:15]
	v_mfma_f32_16x16x32_bf16 v[4:7], v[150:153], v[186:189], v[4:7]
	v_mfma_f32_16x16x32_bf16 v[60:63], v[146:149], v[162:165], v[60:63]
	v_mfma_f32_16x16x32_bf16 v[52:55], v[154:157], v[162:165], v[52:55]
	v_mfma_f32_16x16x32_bf16 v[44:47], v[146:149], v[170:173], v[44:47]
	v_mfma_f32_16x16x32_bf16 v[36:39], v[154:157], v[170:173], v[36:39]
	v_mfma_f32_16x16x32_bf16 v[28:31], v[146:149], v[182:185], v[28:31]
	v_mfma_f32_16x16x32_bf16 v[20:23], v[154:157], v[182:185], v[20:23]
	v_mfma_f32_16x16x32_bf16 v[12:15], v[146:149], v[190:193], v[12:15]
	v_mfma_f32_16x16x32_bf16 v[4:7], v[154:157], v[190:193], v[4:7]
	s_barrier
; __device__ __forceinline__ unsigned cvtpk(float lo, float hi) { const f32x2 v = (f32x2){lo, hi}; const bf16v2 b = __builtin_convertvector(v, bf16v2); return __builtin_bit_cast(unsigned, b); }
; __device__ __forceinline__ float siluf_(float x) { return x * sigmoidf_(x); }
; #define PG8_STAGE(bufoff, gbase, voff) do { _Pragma("unroll") for (int _i = 0; _i < 2; ++_i) \
;         __builtin_amdgcn_global_load_lds((const unsigned*)((const char*)(gbase) + (voff)[_i]), (PG8_LAS unsigned*)(lds + (bufoff) + ldsw + _i * 8192), 16, 0, 0); } while (0)
; #define PG8_MMA(ai, bj, At, Bt) do { __builtin_amdgcn_s_setprio(1); _Pragma("unroll") for (int m = 0; m < 4; ++m) _Pragma("unroll") for (int n = 0; n < 2; ++n) _Pragma("unroll") for (int k = 0; k < 2; ++k) \
;         acc[ai][bj][m][n] = __builtin_amdgcn_mfma_f32_16x16x32_bf16(Bt[n][k], At[m][k], acc[ai][bj][m][n], 0, 0, 0); __builtin_amdgcn_s_setprio(0); } while (0)
; #define PG8_WAIT_V(n) asm volatile("s_waitcnt vmcnt(" #n ")" ::: "memory")
; #define PG8_BAR __builtin_amdgcn_s_barrier()
; template <class Epi, class Sched>
; __device__ __forceinline__ void gemm_phase(PG8_LAS unsigned char* lds, const Gemm g, const Sched& S, const Epi& E) {
;     ...
;             PG8_STAGE(PG8_SB(1, 1), b3 + hstep, voffB);
;             PG8_WAIT_V(6); PG8_BAR; PG8_MMA(1, 1, At, B1); PG8_BAR;
;     __device__ __forceinline__ void operator()(const f32x4 (&acc)[2][2][4][2], const pg8::Unit& u, int wr, int wc, int fr, int fq) const {
;         const int row0 = u.pm * 256 + wr * 64 + fr, col0 = u.pn * 128 + wc * 32 + 8 * fq;
; #pragma unroll
;         for (int ai = 0; ai < 2; ++ai)
; #pragma unroll
;             for (int m = 0; m < 4; ++m) { bf16_t* rowp = O + (size_t)(row0 + ai * 128 + m * 16) * ldc + col0;
;                 const f32x4 g0 = acc[ai][0][m][0], g1 = acc[ai][0][m][1], u0 = acc[ai][1][m][0], u1 = acc[ai][1][m][1];
;                 u32x4 w; w.x = cvtpk(siluf_(g0[0]) * u0[0], siluf_(g0[1]) * u0[1]); w.y = cvtpk(siluf_(g0[2]) * u0[2], siluf_(g0[3]) * u0[3]);
;                 w.z = cvtpk(siluf_(g1[0]) * u1[0], siluf_(g1[1]) * u1[1]); w.w = cvtpk(siluf_(g1[2]) * u1[2], siluf_(g1[3]) * u1[3]);
;                 *(u32x4*)rowp = w; }
	s_add_u32 s14, s14, 0x40080
	s_addc_u32 s15, s15, 0
	s_add_i32 m0, s20, 0x1c000
	s_nop 0
	global_load_lds_dwordx4 v176, s[14:15]
	s_add_i32 m0, s20, 0x1e000
	s_nop 0
	global_load_lds_dwordx4 v128, s[14:15]
	s_waitcnt vmcnt(6)
	s_barrier
	v_mfma_f32_16x16x32_bf16 v[56:59], v[194:197], v[158:161], v[56:59]
	v_mfma_f32_16x16x32_bf16 v[48:51], v[202:205], v[158:161], v[48:51]
	v_mfma_f32_16x16x32_bf16 v[40:43], v[194:197], v[166:169], v[40:43]
	v_mfma_f32_16x16x32_bf16 v[32:35], v[202:205], v[166:169], v[32:35]
	v_mfma_f32_16x16x32_bf16 v[24:27], v[194:197], v[178:181], v[24:27]
	v_mfma_f32_16x16x32_bf16 v[16:19], v[202:205], v[178:181], v[16:19]
	v_mfma_f32_16x16x32_bf16 v[8:11], v[194:197], v[186:189], v[8:11]
	v_mfma_f32_16x16x32_bf16 v[0:3], v[202:205], v[186:189], v[0:3]
	v_mfma_f32_16x16x32_bf16 v[56:59], v[198:201], v[162:165], v[56:59]
	v_mfma_f32_16x16x32_bf16 v[48:51], v[206:209], v[162:165], v[48:51]
	v_mfma_f32_16x16x32_bf16 v[40:43], v[198:201], v[170:173], v[40:43]
	v_mfma_f32_16x16x32_bf16 v[32:35], v[206:209], v[170:173], v[32:35]
	v_mfma_f32_16x16x32_bf16 v[24:27], v[198:201], v[182:185], v[24:27]
	v_mfma_f32_16x16x32_bf16 v[16:19], v[206:209], v[182:185], v[16:19]
	v_mfma_f32_16x16x32_bf16 v[8:11], v[198:201], v[190:193], v[8:11]
	v_mfma_f32_16x16x32_bf16 v[0:3], v[206:209], v[190:193], v[0:3]
	s_add_i32 s45, s45, 2
	s_add_u32 s12, s12, 0x100
	s_addc_u32 s13, s13, 0
	s_add_u32 s43, s43, 0x100
	s_addc_u32 s44, s44, 0
	s_cmp_gt_u32 s45, 13
	s_barrier
	s_cbranch_scc0 .LBB0_114
	v_mul_f32_e32 v147, 0xbfb8aa3b, v124
	v_exp_f32_e32 v147, v147
	v_readlane_b32 s12, v253, 16
	v_lshl_add_u32 v146, s10, 8, v142
	v_lshl_or_b32 v140, s34, 7, v144
	v_add_f32_e32 v147, 1.0, v147
	v_rcp_f32_e32 v150, v147
	v_mul_f32_e32 v147, 0xbfb8aa3b, v125
	v_exp_f32_e32 v147, v147
	v_readlane_b32 s13, v253, 17
	v_ashrrev_i32_e32 v141, 31, v140
	v_lshlrev_b64 v[140:141], 1, v[140:141]
	v_add_f32_e32 v147, 1.0, v147
	v_rcp_f32_e32 v151, v147
	v_mov_b64_e32 v[138:139], s[12:13]
	v_mad_i64_i32 v[148:149], s[12:13], v146, s81, v[138:139]
	v_pk_mul_f32 v[124:125], v[124:125], v[150:151]
	v_lshl_add_u64 v[148:149], v[148:149], 0, v[140:141]
	v_pk_mul_f32 v[120:121], v[124:125], v[120:121]
	s_and_b64 vcc, exec, s[38:39]
	v_cvt_pk_bf16_f32 v120, v120, v121
	v_mul_f32_e32 v121, 0xbfb8aa3b, v126
	v_exp_f32_e32 v121, v121
	s_mov_b32 s34, s0
	s_mov_b32 s10, s4
	s_mov_b64 s[14:15], s[8:9]
	v_add_f32_e32 v121, 1.0, v121
	v_rcp_f32_e32 v124, v121
	v_mul_f32_e32 v121, 0xbfb8aa3b, v127
	v_exp_f32_e32 v121, v121
	s_nop 0
	v_add_f32_e32 v121, 1.0, v121
	v_rcp_f32_e32 v125, v121
	s_nop 0
	v_pk_mul_f32 v[124:125], v[126:127], v[124:125]
	s_nop 0
	v_pk_mul_f32 v[122:123], v[124:125], v[122:123]
	s_nop 0
	v_cvt_pk_bf16_f32 v121, v122, v123
	v_mul_f32_e32 v122, 0xbfb8aa3b, v116
	v_mul_f32_e32 v123, 0xbfb8aa3b, v117
	v_exp_f32_e32 v122, v122
	v_exp_f32_e32 v123, v123
	v_add_f32_e32 v122, 1.0, v122
	v_add_f32_e32 v123, 1.0, v123
	v_rcp_f32_e32 v122, v122
	v_rcp_f32_e32 v123, v123
	s_nop 0
	v_pk_mul_f32 v[116:117], v[116:117], v[122:123]
	s_nop 0
	v_pk_mul_f32 v[112:113], v[116:117], v[112:113]
	s_nop 0
	v_cvt_pk_bf16_f32 v122, v112, v113
	v_mul_f32_e32 v112, 0xbfb8aa3b, v118
	v_mul_f32_e32 v113, 0xbfb8aa3b, v119
	v_exp_f32_e32 v112, v112
	v_exp_f32_e32 v113, v113
	v_add_f32_e32 v112, 1.0, v112
	v_add_f32_e32 v113, 1.0, v113
	v_rcp_f32_e32 v112, v112
	v_rcp_f32_e32 v113, v113
	s_nop 0
	v_pk_mul_f32 v[112:113], v[118:119], v[112:113]
	s_nop 0
	v_pk_mul_f32 v[112:113], v[112:113], v[114:115]
	v_mul_f32_e32 v114, 0xbfb8aa3b, v108
	v_mul_f32_e32 v115, 0xbfb8aa3b, v109
	v_exp_f32_e32 v114, v114
	v_exp_f32_e32 v115, v115
	v_cvt_pk_bf16_f32 v123, v112, v113
	v_or_b32_e32 v112, 16, v146
	v_add_f32_e32 v114, 1.0, v114
	v_add_f32_e32 v115, 1.0, v115
	v_rcp_f32_e32 v114, v114
	v_rcp_f32_e32 v115, v115
	v_mad_i64_i32 v[112:113], s[12:13], v112, s81, v[138:139]
	v_lshl_add_u64 v[112:113], v[112:113], 0, v[140:141]
	v_pk_mul_f32 v[108:109], v[108:109], v[114:115]
	global_store_dwordx4 v[148:149], v[120:123], off
	v_pk_mul_f32 v[104:105], v[108:109], v[104:105]
	s_nop 0
	v_cvt_pk_bf16_f32 v104, v104, v105
	v_mul_f32_e32 v105, 0xbfb8aa3b, v110
	v_exp_f32_e32 v105, v105
	s_nop 0
	v_add_f32_e32 v105, 1.0, v105
	v_rcp_f32_e32 v108, v105
	v_mul_f32_e32 v105, 0xbfb8aa3b, v111
	v_exp_f32_e32 v105, v105
	s_nop 0
	v_add_f32_e32 v105, 1.0, v105
	v_rcp_f32_e32 v109, v105
	s_nop 0
	v_pk_mul_f32 v[108:109], v[110:111], v[108:109]
	s_nop 0
	v_pk_mul_f32 v[106:107], v[108:109], v[106:107]
	s_nop 0
	v_cvt_pk_bf16_f32 v105, v106, v107
	v_mul_f32_e32 v106, 0xbfb8aa3b, v100
	v_mul_f32_e32 v107, 0xbfb8aa3b, v101
	v_exp_f32_e32 v106, v106
	v_exp_f32_e32 v107, v107
	v_add_f32_e32 v106, 1.0, v106
	v_add_f32_e32 v107, 1.0, v107
	v_rcp_f32_e32 v106, v106
	v_rcp_f32_e32 v107, v107
	s_nop 0
	v_pk_mul_f32 v[100:101], v[100:101], v[106:107]
	s_nop 0
	v_pk_mul_f32 v[96:97], v[100:101], v[96:97]
	s_nop 0
	v_cvt_pk_bf16_f32 v106, v96, v97
	v_mul_f32_e32 v96, 0xbfb8aa3b, v102
	v_mul_f32_e32 v97, 0xbfb8aa3b, v103
	v_exp_f32_e32 v96, v96
	v_exp_f32_e32 v97, v97
	v_add_f32_e32 v96, 1.0, v96
	v_add_f32_e32 v97, 1.0, v97
	v_rcp_f32_e32 v96, v96
	v_rcp_f32_e32 v97, v97
	s_nop 0
	v_pk_mul_f32 v[96:97], v[102:103], v[96:97]
	s_nop 0
	v_pk_mul_f32 v[96:97], v[96:97], v[98:99]
	v_mul_f32_e32 v98, 0xbfb8aa3b, v92
	v_mul_f32_e32 v99, 0xbfb8aa3b, v93
	v_exp_f32_e32 v98, v98
	v_exp_f32_e32 v99, v99
	v_cvt_pk_bf16_f32 v107, v96, v97
	v_or_b32_e32 v96, 32, v146
	v_add_f32_e32 v98, 1.0, v98
	v_add_f32_e32 v99, 1.0, v99
	v_rcp_f32_e32 v98, v98
	v_rcp_f32_e32 v99, v99
	v_mad_i64_i32 v[96:97], s[12:13], v96, s81, v[138:139]
; __device__ __forceinline__ unsigned cvtpk(float lo, float hi) { const f32x2 v = (f32x2){lo, hi}; const bf16v2 b = __builtin_convertvector(v, bf16v2); return __builtin_bit_cast(unsigned, b); }
; __device__ __forceinline__ float sigmoidf_(float x) { return __builtin_amdgcn_rcpf(1.0f + __expf(-x)); }
; __device__ __forceinline__ float siluf_(float x) { return x * sigmoidf_(x); }
;     __device__ __forceinline__ void operator()(const f32x4 (&acc)[2][2][4][2], const pg8::Unit& u, int wr, int wc, int fr, int fq) const {
;     ...
;             for (int m = 0; m < 4; ++m) { bf16_t* rowp = O + (size_t)(row0 + ai * 128 + m * 16) * ldc + col0;
;                 const f32x4 g0 = acc[ai][0][m][0], g1 = acc[ai][0][m][1], u0 = acc[ai][1][m][0], u1 = acc[ai][1][m][1];
;                 u32x4 w; w.x = cvtpk(siluf_(g0[0]) * u0[0], siluf_(g0[1]) * u0[1]); w.y = cvtpk(siluf_(g0[2]) * u0[2], siluf_(g0[3]) * u0[3]);
;                 w.z = cvtpk(siluf_(g1[0]) * u1[0], siluf_(g1[1]) * u1[1]); w.w = cvtpk(siluf_(g1[2]) * u1[2], siluf_(g1[3]) * u1[3]);
;                 *(u32x4*)rowp = w; }
	v_lshl_add_u64 v[96:97], v[96:97], 0, v[140:141]
	v_pk_mul_f32 v[92:93], v[92:93], v[98:99]
	global_store_dwordx4 v[112:113], v[104:107], off
	v_pk_mul_f32 v[88:89], v[92:93], v[88:89]
	s_nop 0
	v_cvt_pk_bf16_f32 v88, v88, v89
	v_mul_f32_e32 v89, 0xbfb8aa3b, v94
	v_exp_f32_e32 v89, v89
	s_nop 0
	v_add_f32_e32 v89, 1.0, v89
	v_rcp_f32_e32 v92, v89
	v_mul_f32_e32 v89, 0xbfb8aa3b, v95
	v_exp_f32_e32 v89, v89
	s_nop 0
	v_add_f32_e32 v89, 1.0, v89
	v_rcp_f32_e32 v93, v89
	s_nop 0
	v_pk_mul_f32 v[92:93], v[94:95], v[92:93]
	s_nop 0
	v_pk_mul_f32 v[90:91], v[92:93], v[90:91]
	s_nop 0
	v_cvt_pk_bf16_f32 v89, v90, v91
	v_mul_f32_e32 v90, 0xbfb8aa3b, v84
	v_mul_f32_e32 v91, 0xbfb8aa3b, v85
	v_exp_f32_e32 v90, v90
	v_exp_f32_e32 v91, v91
	v_add_f32_e32 v90, 1.0, v90
	v_add_f32_e32 v91, 1.0, v91
	v_rcp_f32_e32 v90, v90
	v_rcp_f32_e32 v91, v91
	s_nop 0
	v_pk_mul_f32 v[84:85], v[84:85], v[90:91]
	s_nop 0
	v_pk_mul_f32 v[80:81], v[84:85], v[80:81]
	s_nop 0
	v_cvt_pk_bf16_f32 v90, v80, v81
	v_mul_f32_e32 v80, 0xbfb8aa3b, v86
	v_mul_f32_e32 v81, 0xbfb8aa3b, v87
	v_exp_f32_e32 v80, v80
	v_exp_f32_e32 v81, v81
	v_add_f32_e32 v80, 1.0, v80
	v_add_f32_e32 v81, 1.0, v81
	v_rcp_f32_e32 v80, v80
	v_rcp_f32_e32 v81, v81
	s_nop 0
	v_pk_mul_f32 v[80:81], v[86:87], v[80:81]
	s_nop 0
	v_pk_mul_f32 v[80:81], v[80:81], v[82:83]
	v_mul_f32_e32 v82, 0xbfb8aa3b, v76
	v_mul_f32_e32 v83, 0xbfb8aa3b, v77
	v_exp_f32_e32 v82, v82
	v_exp_f32_e32 v83, v83
	v_cvt_pk_bf16_f32 v91, v80, v81
	v_or_b32_e32 v80, 48, v146
	v_add_f32_e32 v82, 1.0, v82
	v_add_f32_e32 v83, 1.0, v83
	v_rcp_f32_e32 v82, v82
	v_rcp_f32_e32 v83, v83
	v_mad_i64_i32 v[80:81], s[12:13], v80, s81, v[138:139]
	v_lshl_add_u64 v[80:81], v[80:81], 0, v[140:141]
	v_pk_mul_f32 v[76:77], v[76:77], v[82:83]
	global_store_dwordx4 v[96:97], v[88:91], off
	v_pk_mul_f32 v[72:73], v[76:77], v[72:73]
	s_nop 0
	v_cvt_pk_bf16_f32 v72, v72, v73
	v_mul_f32_e32 v73, 0xbfb8aa3b, v78
	v_exp_f32_e32 v73, v73
	s_nop 0
	v_add_f32_e32 v73, 1.0, v73
	v_rcp_f32_e32 v76, v73
	v_mul_f32_e32 v73, 0xbfb8aa3b, v79
	v_exp_f32_e32 v73, v73
	s_nop 0
	v_add_f32_e32 v73, 1.0, v73
	v_rcp_f32_e32 v77, v73
	s_nop 0
	v_pk_mul_f32 v[76:77], v[78:79], v[76:77]
	s_nop 0
	v_pk_mul_f32 v[74:75], v[76:77], v[74:75]
	s_nop 0
	v_cvt_pk_bf16_f32 v73, v74, v75
	v_mul_f32_e32 v74, 0xbfb8aa3b, v68
	v_mul_f32_e32 v75, 0xbfb8aa3b, v69
	v_exp_f32_e32 v74, v74
	v_exp_f32_e32 v75, v75
	v_add_f32_e32 v74, 1.0, v74
	v_add_f32_e32 v75, 1.0, v75
	v_rcp_f32_e32 v74, v74
	v_rcp_f32_e32 v75, v75
	s_nop 0
	v_pk_mul_f32 v[68:69], v[68:69], v[74:75]
	s_nop 0
	v_pk_mul_f32 v[64:65], v[68:69], v[64:65]
	s_nop 0
	v_cvt_pk_bf16_f32 v74, v64, v65
	v_mul_f32_e32 v64, 0xbfb8aa3b, v70
	v_mul_f32_e32 v65, 0xbfb8aa3b, v71
	v_exp_f32_e32 v64, v64
	v_exp_f32_e32 v65, v65
	v_add_f32_e32 v64, 1.0, v64
	v_add_f32_e32 v65, 1.0, v65
	v_rcp_f32_e32 v64, v64
	v_rcp_f32_e32 v65, v65
	s_nop 0
	v_pk_mul_f32 v[64:65], v[70:71], v[64:65]
	s_nop 0
	v_pk_mul_f32 v[64:65], v[64:65], v[66:67]
	v_mul_f32_e32 v66, 0xbfb8aa3b, v60
	v_mul_f32_e32 v67, 0xbfb8aa3b, v61
	v_exp_f32_e32 v66, v66
	v_exp_f32_e32 v67, v67
	v_cvt_pk_bf16_f32 v75, v64, v65
	v_add_u32_e32 v64, 0x80, v146
	v_add_f32_e32 v66, 1.0, v66
	v_add_f32_e32 v67, 1.0, v67
	v_rcp_f32_e32 v66, v66
	v_rcp_f32_e32 v67, v67
	v_mad_i64_i32 v[64:65], s[12:13], v64, s81, v[138:139]
	v_lshl_add_u64 v[64:65], v[64:65], 0, v[140:141]
	v_pk_mul_f32 v[60:61], v[60:61], v[66:67]
	global_store_dwordx4 v[80:81], v[72:75], off
	v_pk_mul_f32 v[56:57], v[60:61], v[56:57]
	s_nop 0
	v_cvt_pk_bf16_f32 v56, v56, v57
	v_mul_f32_e32 v57, 0xbfb8aa3b, v62
	v_exp_f32_e32 v57, v57
	s_nop 0
	v_add_f32_e32 v57, 1.0, v57
	v_rcp_f32_e32 v60, v57
	v_mul_f32_e32 v57, 0xbfb8aa3b, v63
	v_exp_f32_e32 v57, v57
	s_nop 0
	v_add_f32_e32 v57, 1.0, v57
	v_rcp_f32_e32 v61, v57
	s_nop 0
	v_pk_mul_f32 v[60:61], v[62:63], v[60:61]
	s_nop 0
	v_pk_mul_f32 v[58:59], v[60:61], v[58:59]
	s_nop 0
	v_cvt_pk_bf16_f32 v57, v58, v59
	v_mul_f32_e32 v58, 0xbfb8aa3b, v52
	v_mul_f32_e32 v59, 0xbfb8aa3b, v53
	v_exp_f32_e32 v58, v58
	v_exp_f32_e32 v59, v59
	v_add_f32_e32 v58, 1.0, v58
	v_add_f32_e32 v59, 1.0, v59
	v_rcp_f32_e32 v58, v58
	v_rcp_f32_e32 v59, v59
	s_nop 0
	v_pk_mul_f32 v[52:53], v[52:53], v[58:59]
	s_nop 0
	v_pk_mul_f32 v[48:49], v[52:53], v[48:49]
	s_nop 0
	v_cvt_pk_bf16_f32 v58, v48, v49
	v_mul_f32_e32 v48, 0xbfb8aa3b, v54
	v_mul_f32_e32 v49, 0xbfb8aa3b, v55
	v_exp_f32_e32 v48, v48
	v_exp_f32_e32 v49, v49
	v_add_f32_e32 v48, 1.0, v48
	v_add_f32_e32 v49, 1.0, v49
	v_rcp_f32_e32 v48, v48
	v_rcp_f32_e32 v49, v49
	s_nop 0
	v_pk_mul_f32 v[48:49], v[54:55], v[48:49]
	s_nop 0
	v_pk_mul_f32 v[48:49], v[48:49], v[50:51]
	v_mul_f32_e32 v50, 0xbfb8aa3b, v44
	v_mul_f32_e32 v51, 0xbfb8aa3b, v45
	v_exp_f32_e32 v50, v50
	v_exp_f32_e32 v51, v51
	v_cvt_pk_bf16_f32 v59, v48, v49
	v_add_u32_e32 v48, 0x90, v146
	v_add_f32_e32 v50, 1.0, v50
	v_add_f32_e32 v51, 1.0, v51
	v_rcp_f32_e32 v50, v50
	v_rcp_f32_e32 v51, v51
; __device__ __forceinline__ unsigned cvtpk(float lo, float hi) { const f32x2 v = (f32x2){lo, hi}; const bf16v2 b = __builtin_convertvector(v, bf16v2); return __builtin_bit_cast(unsigned, b); }
; __device__ __forceinline__ float siluf_(float x) { return x * sigmoidf_(x); }
; #define PG8_WAIT_V(n) asm volatile("s_waitcnt vmcnt(" #n ")" ::: "memory")
; #define PG8_BAR __builtin_amdgcn_s_barrier()
; template <class Epi, class Sched>
; __device__ __forceinline__ void gemm_phase(PG8_LAS unsigned char* lds, const Gemm g, const Sched& S, const Epi& E) {
;     ...
;         if constexpr (!Epi::AFTER_DRAIN) { E(acc, cur, wr, wc, fr, fq); S.done(cur); }
;         if (!has_next) break;
; #pragma unroll
;         for (int a = 0; a < 2; ++a)
; #pragma unroll
;             for (int b = 0; b < 2; ++b)
; #pragma unroll
;                 for (int m = 0; m < 4; ++m)
; #pragma unroll
;                     for (int n = 0; n < 2; ++n) acc[a][b][m][n] = (f32x4){0.f, 0.f, 0.f, 0.f};
;         cur = nxt; cA = nA; cB = nB; ++ui;
;     }
;     PG8_WAIT_V(0);
;     if (wr == 0) PG8_BAR;
;     PG8_BAR;
;     if constexpr (Epi::AFTER_DRAIN) { E.fused(acc, cur, wr, wc, fr, fq, lds, wid, lane); S.done(cur); }
;     __device__ __forceinline__ void operator()(const f32x4 (&acc)[2][2][4][2], const pg8::Unit& u, int wr, int wc, int fr, int fq) const {
;     ...
;             for (int m = 0; m < 4; ++m) { bf16_t* rowp = O + (size_t)(row0 + ai * 128 + m * 16) * ldc + col0;
;                 const f32x4 g0 = acc[ai][0][m][0], g1 = acc[ai][0][m][1], u0 = acc[ai][1][m][0], u1 = acc[ai][1][m][1];
;                 u32x4 w; w.x = cvtpk(siluf_(g0[0]) * u0[0], siluf_(g0[1]) * u0[1]); w.y = cvtpk(siluf_(g0[2]) * u0[2], siluf_(g0[3]) * u0[3]);
;                 w.z = cvtpk(siluf_(g1[0]) * u1[0], siluf_(g1[1]) * u1[1]); w.w = cvtpk(siluf_(g1[2]) * u1[2], siluf_(g1[3]) * u1[3]);
;                 *(u32x4*)rowp = w; }
	v_mad_i64_i32 v[48:49], s[12:13], v48, s81, v[138:139]
	v_lshl_add_u64 v[48:49], v[48:49], 0, v[140:141]
	v_pk_mul_f32 v[44:45], v[44:45], v[50:51]
	global_store_dwordx4 v[64:65], v[56:59], off
	v_pk_mul_f32 v[40:41], v[44:45], v[40:41]
	s_nop 0
	v_cvt_pk_bf16_f32 v40, v40, v41
	v_mul_f32_e32 v41, 0xbfb8aa3b, v46
	v_exp_f32_e32 v41, v41
	s_nop 0
	v_add_f32_e32 v41, 1.0, v41
	v_rcp_f32_e32 v44, v41
	v_mul_f32_e32 v41, 0xbfb8aa3b, v47
	v_exp_f32_e32 v41, v41
	s_nop 0
	v_add_f32_e32 v41, 1.0, v41
	v_rcp_f32_e32 v45, v41
	s_nop 0
	v_pk_mul_f32 v[44:45], v[46:47], v[44:45]
	s_nop 0
	v_pk_mul_f32 v[42:43], v[44:45], v[42:43]
	s_nop 0
	v_cvt_pk_bf16_f32 v41, v42, v43
	v_mul_f32_e32 v42, 0xbfb8aa3b, v36
	v_mul_f32_e32 v43, 0xbfb8aa3b, v37
	v_exp_f32_e32 v42, v42
	v_exp_f32_e32 v43, v43
	v_add_f32_e32 v42, 1.0, v42
	v_add_f32_e32 v43, 1.0, v43
	v_rcp_f32_e32 v42, v42
	v_rcp_f32_e32 v43, v43
	s_nop 0
	v_pk_mul_f32 v[36:37], v[36:37], v[42:43]
	s_nop 0
	v_pk_mul_f32 v[32:33], v[36:37], v[32:33]
	s_nop 0
	v_cvt_pk_bf16_f32 v42, v32, v33
	v_mul_f32_e32 v32, 0xbfb8aa3b, v38
	v_mul_f32_e32 v33, 0xbfb8aa3b, v39
	v_exp_f32_e32 v32, v32
	v_exp_f32_e32 v33, v33
	v_add_f32_e32 v32, 1.0, v32
	v_add_f32_e32 v33, 1.0, v33
	v_rcp_f32_e32 v32, v32
	v_rcp_f32_e32 v33, v33
	s_nop 0
	v_pk_mul_f32 v[32:33], v[38:39], v[32:33]
	s_nop 0
	v_pk_mul_f32 v[32:33], v[32:33], v[34:35]
	v_mul_f32_e32 v34, 0xbfb8aa3b, v28
	v_mul_f32_e32 v35, 0xbfb8aa3b, v29
	v_exp_f32_e32 v34, v34
	v_exp_f32_e32 v35, v35
	v_cvt_pk_bf16_f32 v43, v32, v33
	v_add_u32_e32 v32, 0xa0, v146
	v_add_f32_e32 v34, 1.0, v34
	v_add_f32_e32 v35, 1.0, v35
	v_rcp_f32_e32 v34, v34
	v_rcp_f32_e32 v35, v35
	v_mad_i64_i32 v[32:33], s[12:13], v32, s81, v[138:139]
	v_lshl_add_u64 v[32:33], v[32:33], 0, v[140:141]
	v_pk_mul_f32 v[28:29], v[28:29], v[34:35]
	global_store_dwordx4 v[48:49], v[40:43], off
	v_pk_mul_f32 v[24:25], v[28:29], v[24:25]
	s_nop 0
	v_cvt_pk_bf16_f32 v24, v24, v25
	v_mul_f32_e32 v25, 0xbfb8aa3b, v30
	v_exp_f32_e32 v25, v25
	s_nop 0
	v_add_f32_e32 v25, 1.0, v25
	v_rcp_f32_e32 v28, v25
	v_mul_f32_e32 v25, 0xbfb8aa3b, v31
	v_exp_f32_e32 v25, v25
	s_nop 0
	v_add_f32_e32 v25, 1.0, v25
	v_rcp_f32_e32 v29, v25
	s_nop 0
	v_pk_mul_f32 v[28:29], v[30:31], v[28:29]
	s_nop 0
	v_pk_mul_f32 v[26:27], v[28:29], v[26:27]
	s_nop 0
	v_cvt_pk_bf16_f32 v25, v26, v27
	v_mul_f32_e32 v26, 0xbfb8aa3b, v20
	v_mul_f32_e32 v27, 0xbfb8aa3b, v21
	v_exp_f32_e32 v26, v26
	v_exp_f32_e32 v27, v27
	v_add_f32_e32 v26, 1.0, v26
	v_add_f32_e32 v27, 1.0, v27
	v_rcp_f32_e32 v26, v26
	v_rcp_f32_e32 v27, v27
	s_nop 0
	v_pk_mul_f32 v[20:21], v[20:21], v[26:27]
	s_nop 0
	v_pk_mul_f32 v[16:17], v[20:21], v[16:17]
	s_nop 0
	v_cvt_pk_bf16_f32 v26, v16, v17
	v_mul_f32_e32 v16, 0xbfb8aa3b, v22
	v_mul_f32_e32 v17, 0xbfb8aa3b, v23
	v_exp_f32_e32 v16, v16
	v_exp_f32_e32 v17, v17
	v_add_f32_e32 v16, 1.0, v16
	v_add_f32_e32 v17, 1.0, v17
	v_rcp_f32_e32 v16, v16
	v_rcp_f32_e32 v17, v17
	s_nop 0
	v_pk_mul_f32 v[16:17], v[22:23], v[16:17]
	s_nop 0
	v_pk_mul_f32 v[16:17], v[16:17], v[18:19]
	v_mul_f32_e32 v18, 0xbfb8aa3b, v12
	v_mul_f32_e32 v19, 0xbfb8aa3b, v13
	v_exp_f32_e32 v18, v18
	v_exp_f32_e32 v19, v19
	v_cvt_pk_bf16_f32 v27, v16, v17
	v_add_u32_e32 v16, 0xb0, v146
	v_add_f32_e32 v18, 1.0, v18
	v_add_f32_e32 v19, 1.0, v19
	v_rcp_f32_e32 v18, v18
	v_rcp_f32_e32 v19, v19
	v_mad_i64_i32 v[16:17], s[12:13], v16, s81, v[138:139]
	v_lshl_add_u64 v[16:17], v[16:17], 0, v[140:141]
	v_pk_mul_f32 v[12:13], v[12:13], v[18:19]
	s_mov_b64 s[12:13], s[6:7]
	v_pk_mul_f32 v[8:9], v[12:13], v[8:9]
	global_store_dwordx4 v[32:33], v[24:27], off
	v_cvt_pk_bf16_f32 v8, v8, v9
	v_mul_f32_e32 v9, 0xbfb8aa3b, v14
	v_exp_f32_e32 v9, v9
	s_nop 0
	v_add_f32_e32 v9, 1.0, v9
	v_rcp_f32_e32 v12, v9
	v_mul_f32_e32 v9, 0xbfb8aa3b, v15
	v_exp_f32_e32 v9, v9
	s_nop 0
	v_add_f32_e32 v9, 1.0, v9
	v_rcp_f32_e32 v13, v9
	s_nop 0
	v_pk_mul_f32 v[12:13], v[14:15], v[12:13]
	s_nop 0
	v_pk_mul_f32 v[10:11], v[12:13], v[10:11]
	s_nop 0
	v_cvt_pk_bf16_f32 v9, v10, v11
	v_mul_f32_e32 v10, 0xbfb8aa3b, v4
	v_mul_f32_e32 v11, 0xbfb8aa3b, v5
	v_exp_f32_e32 v10, v10
	v_exp_f32_e32 v11, v11
	v_add_f32_e32 v10, 1.0, v10
	v_add_f32_e32 v11, 1.0, v11
	v_rcp_f32_e32 v10, v10
	v_rcp_f32_e32 v11, v11
	s_nop 0
	v_pk_mul_f32 v[4:5], v[4:5], v[10:11]
	s_nop 0
	v_pk_mul_f32 v[0:1], v[4:5], v[0:1]
	s_nop 0
	v_cvt_pk_bf16_f32 v10, v0, v1
	v_mul_f32_e32 v0, 0xbfb8aa3b, v6
	v_mul_f32_e32 v1, 0xbfb8aa3b, v7
	v_exp_f32_e32 v0, v0
	v_exp_f32_e32 v1, v1
	v_add_f32_e32 v0, 1.0, v0
	v_add_f32_e32 v1, 1.0, v1
	v_rcp_f32_e32 v0, v0
	v_rcp_f32_e32 v1, v1
	s_nop 0
	v_pk_mul_f32 v[0:1], v[6:7], v[0:1]
	s_nop 0
	v_pk_mul_f32 v[0:1], v[0:1], v[2:3]
	s_nop 0
	v_cvt_pk_bf16_f32 v11, v0, v1
	global_store_dwordx4 v[16:17], v[8:11], off
	s_cbranch_vccz .LBB0_111
	s_waitcnt vmcnt(0)
	v_readlane_b32 s22, v255, 14
	s_cmpk_gt_u32 s19, 0xff
	v_readlane_b32 s23, v255, 15
	s_mov_b64 s[28:29], s[54:55]
	s_cbranch_scc1 .LBB0_118
	s_barrier

; #define PG8_STAGE(bufoff, gbase, voff) do { _Pragma("unroll") for (int _i = 0; _i < 2; ++_i) \
;         __builtin_amdgcn_global_load_lds((const unsigned*)((const char*)(gbase) + (voff)[_i]), (PG8_LAS unsigned*)(lds + (bufoff) + ldsw + _i * 8192), 16, 0, 0); } while (0)
; #define PG8_LDA(dst, b, h) do { _Pragma("unroll") for (int m = 0; m < 4; ++m) _Pragma("unroll") for (int k = 0; k < 2; ++k) dst[m][k] = *(const PG8_LAS bf16x8*)(lds + PG8_SA(b, h) + aoff + m * 2048 + k * 1024); } while (0)
; #define PG8_LDB(dst, b, h) do { _Pragma("unroll") for (int n = 0; n < 2; ++n) _Pragma("unroll") for (int k = 0; k < 2; ++k) dst[n][k] = *(const PG8_LAS bf16x8*)(lds + PG8_SB(b, h) + boff + n * 2048 + k * 1024); } while (0)
; #define PG8_MMA(ai, bj, At, Bt) do { __builtin_amdgcn_s_setprio(1); _Pragma("unroll") for (int m = 0; m < 4; ++m) _Pragma("unroll") for (int n = 0; n < 2; ++n) _Pragma("unroll") for (int k = 0; k < 2; ++k) \
;         acc[ai][bj][m][n] = __builtin_amdgcn_mfma_f32_16x16x32_bf16(Bt[n][k], At[m][k], acc[ai][bj][m][n], 0, 0, 0); __builtin_amdgcn_s_setprio(0); } while (0)
; #define PG8_WAIT_V(n) asm volatile("s_waitcnt vmcnt(" #n ")" ::: "memory")
; template <class Epi, class Sched>
; __device__ __forceinline__ void gemm_phase(PG8_LAS unsigned char* lds, const Gemm g, const Sched& S, const Epi& E) {
;     ...
;         for (int t = 0; t < nt; t += 2) {
;             const bool last = (t == nt - 2);
;             const char* a1 = cA + (size_t)(t + 1) * kstep;
;             const char* a2 = last ? nA : cA + (size_t)(t + 2) * kstep; const char* b2 = last ? nB : cB + (size_t)(t + 2) * kstep;
;             const char* a3 = a2 + kstep; const char* b3 = b2 + kstep;
;             if (last && has_next) S.a_ready(nxt);
;             PG8_LDB(B0, 0, 0); PG8_SCHED; PG8_LDA(At, 0, 0); PG8_STAGE(PG8_SA(1, 1), a1 + hstep, voffA);
;             PG8_WAIT_L(8); PG8_BAR; PG8_WAIT_L(0); PG8_MMA(0, 0, At, B0); PG8_BAR; PG8_SCHED;
;             PG8_LDB(B1, 0, 1); PG8_STAGE(PG8_SB(0, 0), b2, voffB);
;             PG8_BAR; PG8_WAIT_L(0); PG8_MMA(0, 1, At, B1); PG8_BAR;
;             PG8_LDA(At, 0, 1); PG8_STAGE(PG8_SA(0, 0), a2, voffA);
;             PG8_BAR; PG8_WAIT_L(0); PG8_MMA(1, 0, At, B0); PG8_BAR; PG8_SCHED;
;             PG8_STAGE(PG8_SB(0, 1), b2 + hstep, voffB);
;             PG8_WAIT_V(6); PG8_BAR; PG8_MMA(1, 1, At, B1); PG8_BAR;
.LBB0_137:
	s_add_u32 s14, s12, 0xfffc0080
	s_addc_u32 s15, s13, -1
	v_add_u32_e32 v154, 0x10000, v139
	ds_read_b128 v[142:145], v154
	ds_read_b128 v[146:149], v154 offset:1024
	ds_read_b128 v[150:153], v154 offset:2048
	ds_read_b128 v[154:157], v154 offset:3072
	s_cmp_eq_u32 s45, 12
	s_cselect_b32 s17, s7, s15
	s_cselect_b32 s16, s40, s14
	s_cselect_b32 s15, s5, s44
	s_cselect_b32 s14, s41, s43
	s_add_i32 m0, s1, 0xc000
	ds_read_b128 v[158:161], v141
	ds_read_b128 v[162:165], v141 offset:1024
	ds_read_b128 v[166:169], v141 offset:2048
	ds_read_b128 v[170:173], v141 offset:3072
	ds_read_b128 v[178:181], v141 offset:4096
	ds_read_b128 v[182:185], v141 offset:5120
	ds_read_b128 v[186:189], v141 offset:6144
	global_load_lds_dwordx4 v134, s[12:13]
	s_add_i32 m0, s1, 0xe000
	ds_read_b128 v[190:193], v141 offset:7168
	global_load_lds_dwordx4 v136, s[12:13]
	s_waitcnt lgkmcnt(8)
	s_barrier
	s_waitcnt lgkmcnt(0)
	v_mfma_f32_16x16x32_bf16 v[124:127], v[142:145], v[158:161], v[124:127]
	v_mfma_f32_16x16x32_bf16 v[120:123], v[150:153], v[158:161], v[120:123]
	v_mfma_f32_16x16x32_bf16 v[116:119], v[142:145], v[166:169], v[116:119]
	v_mfma_f32_16x16x32_bf16 v[112:115], v[150:153], v[166:169], v[112:115]
	v_mfma_f32_16x16x32_bf16 v[100:103], v[142:145], v[178:181], v[100:103]
	v_mfma_f32_16x16x32_bf16 v[96:99], v[150:153], v[178:181], v[96:99]
	v_mfma_f32_16x16x32_bf16 v[84:87], v[142:145], v[186:189], v[84:87]
	v_mfma_f32_16x16x32_bf16 v[80:83], v[150:153], v[186:189], v[80:83]
	v_mfma_f32_16x16x32_bf16 v[124:127], v[146:149], v[162:165], v[124:127]
	v_mfma_f32_16x16x32_bf16 v[120:123], v[154:157], v[162:165], v[120:123]
	v_mfma_f32_16x16x32_bf16 v[116:119], v[146:149], v[170:173], v[116:119]
	v_mfma_f32_16x16x32_bf16 v[112:115], v[154:157], v[170:173], v[112:115]
	v_mfma_f32_16x16x32_bf16 v[100:103], v[146:149], v[182:185], v[100:103]
	v_mfma_f32_16x16x32_bf16 v[96:99], v[154:157], v[182:185], v[96:99]
	v_mfma_f32_16x16x32_bf16 v[84:87], v[146:149], v[190:193], v[84:87]
	v_mfma_f32_16x16x32_bf16 v[80:83], v[154:157], v[190:193], v[80:83]
	s_barrier
	s_add_i32 s48, 0, 0x14000
	v_add_u32_e32 v174, 0x14000, v139
	ds_read_b128 v[194:197], v174
	ds_read_b128 v[198:201], v174 offset:1024
	s_add_u32 s98, s14, 0x80
	s_addc_u32 s99, s15, 0
	s_add_i32 m0, s20, 0x10000
	ds_read_b128 v[202:205], v174 offset:2048
	global_load_lds_dwordx4 v176, s[14:15]
	s_add_i32 m0, s20, 0x12000
	ds_read_b128 v[206:209], v174 offset:3072
	global_load_lds_dwordx4 v128, s[14:15]
	s_barrier
	s_waitcnt lgkmcnt(0)
	v_mfma_f32_16x16x32_bf16 v[108:111], v[194:197], v[158:161], v[108:111]
	v_mfma_f32_16x16x32_bf16 v[104:107], v[202:205], v[158:161], v[104:107]
	v_mfma_f32_16x16x32_bf16 v[92:95], v[194:197], v[166:169], v[92:95]
	v_mfma_f32_16x16x32_bf16 v[88:91], v[202:205], v[166:169], v[88:91]
	v_mfma_f32_16x16x32_bf16 v[76:79], v[194:197], v[178:181], v[76:79]
	v_mfma_f32_16x16x32_bf16 v[72:75], v[202:205], v[178:181], v[72:75]
	v_mfma_f32_16x16x32_bf16 v[68:71], v[194:197], v[186:189], v[68:71]
	v_mfma_f32_16x16x32_bf16 v[64:67], v[202:205], v[186:189], v[64:67]
	v_mfma_f32_16x16x32_bf16 v[108:111], v[198:201], v[162:165], v[108:111]
	v_mfma_f32_16x16x32_bf16 v[104:107], v[206:209], v[162:165], v[104:107]
	v_mfma_f32_16x16x32_bf16 v[92:95], v[198:201], v[170:173], v[92:95]
	v_mfma_f32_16x16x32_bf16 v[88:91], v[206:209], v[170:173], v[88:91]
	v_mfma_f32_16x16x32_bf16 v[76:79], v[198:201], v[182:185], v[76:79]
	v_mfma_f32_16x16x32_bf16 v[72:75], v[206:209], v[182:185], v[72:75]
	v_mfma_f32_16x16x32_bf16 v[68:71], v[198:201], v[190:193], v[68:71]
	v_mfma_f32_16x16x32_bf16 v[64:67], v[206:209], v[190:193], v[64:67]
	s_mov_b32 m0, s1
	s_add_u32 s100, s16, 0x80
	s_addc_u32 s101, s17, 0
	s_barrier
	ds_read_b128 v[158:161], v141 offset:16384
	ds_read_b128 v[162:165], v141 offset:17408
	ds_read_b128 v[166:169], v141 offset:18432
	ds_read_b128 v[170:173], v141 offset:19456
	ds_read_b128 v[178:181], v141 offset:20480
	ds_read_b128 v[182:185], v141 offset:21504
	ds_read_b128 v[186:189], v141 offset:22528
	global_load_lds_dwordx4 v132, s[16:17]
	s_mov_b32 m0, s22
	ds_read_b128 v[190:193], v141 offset:23552
	global_load_lds_dwordx4 v130, s[16:17]
	s_barrier
	s_waitcnt lgkmcnt(0)
	v_mfma_f32_16x16x32_bf16 v[60:63], v[142:145], v[158:161], v[60:63]
	v_mfma_f32_16x16x32_bf16 v[56:59], v[150:153], v[158:161], v[56:59]
	v_mfma_f32_16x16x32_bf16 v[52:55], v[142:145], v[166:169], v[52:55]
	v_mfma_f32_16x16x32_bf16 v[48:51], v[150:153], v[166:169], v[48:51]
	v_mfma_f32_16x16x32_bf16 v[36:39], v[142:145], v[178:181], v[36:39]
	v_mfma_f32_16x16x32_bf16 v[32:35], v[150:153], v[178:181], v[32:35]
	v_mfma_f32_16x16x32_bf16 v[20:23], v[142:145], v[186:189], v[20:23]
	v_mfma_f32_16x16x32_bf16 v[16:19], v[150:153], v[186:189], v[16:19]
	v_mfma_f32_16x16x32_bf16 v[60:63], v[146:149], v[162:165], v[60:63]
	v_mfma_f32_16x16x32_bf16 v[56:59], v[154:157], v[162:165], v[56:59]
	v_mfma_f32_16x16x32_bf16 v[52:55], v[146:149], v[170:173], v[52:55]
	v_mfma_f32_16x16x32_bf16 v[48:51], v[154:157], v[170:173], v[48:51]
	v_mfma_f32_16x16x32_bf16 v[36:39], v[146:149], v[182:185], v[36:39]
	v_mfma_f32_16x16x32_bf16 v[32:35], v[154:157], v[182:185], v[32:35]
	v_mfma_f32_16x16x32_bf16 v[20:23], v[146:149], v[190:193], v[20:23]
	v_mfma_f32_16x16x32_bf16 v[16:19], v[154:157], v[190:193], v[16:19]
	s_barrier
	s_add_u32 s46, s14, 0x40000
	s_addc_u32 s47, s15, 0
	s_add_i32 m0, s20, 0x14000
	s_nop 0
	global_load_lds_dwordx4 v176, s[46:47]
	s_add_i32 m0, s20, 0x16000
	s_nop 0
	global_load_lds_dwordx4 v128, s[46:47]
	s_waitcnt vmcnt(6)
	s_barrier
; #define PG8_STAGE(bufoff, gbase, voff) do { _Pragma("unroll") for (int _i = 0; _i < 2; ++_i) \
;         __builtin_amdgcn_global_load_lds((const unsigned*)((const char*)(gbase) + (voff)[_i]), (PG8_LAS unsigned*)(lds + (bufoff) + ldsw + _i * 8192), 16, 0, 0); } while (0)
; #define PG8_LDA(dst, b, h) do { _Pragma("unroll") for (int m = 0; m < 4; ++m) _Pragma("unroll") for (int k = 0; k < 2; ++k) dst[m][k] = *(const PG8_LAS bf16x8*)(lds + PG8_SA(b, h) + aoff + m * 2048 + k * 1024); } while (0)
; #define PG8_LDB(dst, b, h) do { _Pragma("unroll") for (int n = 0; n < 2; ++n) _Pragma("unroll") for (int k = 0; k < 2; ++k) dst[n][k] = *(const PG8_LAS bf16x8*)(lds + PG8_SB(b, h) + boff + n * 2048 + k * 1024); } while (0)
; #define PG8_MMA(ai, bj, At, Bt) do { __builtin_amdgcn_s_setprio(1); _Pragma("unroll") for (int m = 0; m < 4; ++m) _Pragma("unroll") for (int n = 0; n < 2; ++n) _Pragma("unroll") for (int k = 0; k < 2; ++k) \
;         acc[ai][bj][m][n] = __builtin_amdgcn_mfma_f32_16x16x32_bf16(Bt[n][k], At[m][k], acc[ai][bj][m][n], 0, 0, 0); __builtin_amdgcn_s_setprio(0); } while (0)
; #define PG8_WAIT_V(n) asm volatile("s_waitcnt vmcnt(" #n ")" ::: "memory")
; #define PG8_WAIT_L(n) asm volatile("s_waitcnt lgkmcnt(" #n ")" ::: "memory")
; #define PG8_BAR __builtin_amdgcn_s_barrier()
; #define PG8_SCHED __builtin_amdgcn_sched_barrier(0)
; template <class Epi, class Sched>
; __device__ __forceinline__ void gemm_phase(PG8_LAS unsigned char* lds, const Gemm g, const Sched& S, const Epi& E) {
;     ...
;             PG8_WAIT_V(6); PG8_BAR; PG8_MMA(1, 1, At, B1); PG8_BAR;
;             PG8_LDB(B0, 1, 0); PG8_SCHED; PG8_LDA(At, 1, 0); PG8_STAGE(PG8_SA(0, 1), a2 + hstep, voffA);
;             PG8_WAIT_L(8); PG8_BAR; PG8_WAIT_L(0); PG8_MMA(0, 0, At, B0); PG8_BAR; PG8_SCHED;
;             PG8_LDB(B1, 1, 1); PG8_STAGE(PG8_SB(1, 0), b3, voffB);
;             PG8_BAR; PG8_WAIT_L(0); PG8_MMA(0, 1, At, B1); PG8_BAR;
;             PG8_LDA(At, 1, 1); PG8_STAGE(PG8_SA(1, 0), a3, voffA);
;             PG8_BAR; PG8_WAIT_L(0); PG8_MMA(1, 0, At, B0); PG8_BAR; PG8_SCHED;
	v_mfma_f32_16x16x32_bf16 v[44:47], v[194:197], v[158:161], v[44:47]
	v_mfma_f32_16x16x32_bf16 v[40:43], v[202:205], v[158:161], v[40:43]
	v_mfma_f32_16x16x32_bf16 v[28:31], v[194:197], v[166:169], v[28:31]
	v_mfma_f32_16x16x32_bf16 v[24:27], v[202:205], v[166:169], v[24:27]
	v_mfma_f32_16x16x32_bf16 v[12:15], v[194:197], v[178:181], v[12:15]
	v_mfma_f32_16x16x32_bf16 v[8:11], v[202:205], v[178:181], v[8:11]
	v_mfma_f32_16x16x32_bf16 v[4:7], v[194:197], v[186:189], v[4:7]
	v_mfma_f32_16x16x32_bf16 v[0:3], v[202:205], v[186:189], v[0:3]
	v_mfma_f32_16x16x32_bf16 v[44:47], v[198:201], v[162:165], v[44:47]
	v_mfma_f32_16x16x32_bf16 v[40:43], v[206:209], v[162:165], v[40:43]
	v_mfma_f32_16x16x32_bf16 v[28:31], v[198:201], v[170:173], v[28:31]
	v_mfma_f32_16x16x32_bf16 v[24:27], v[206:209], v[170:173], v[24:27]
	v_mfma_f32_16x16x32_bf16 v[12:15], v[198:201], v[182:185], v[12:15]
	v_mfma_f32_16x16x32_bf16 v[8:11], v[206:209], v[182:185], v[8:11]
	v_mfma_f32_16x16x32_bf16 v[4:7], v[198:201], v[190:193], v[4:7]
	v_mfma_f32_16x16x32_bf16 v[0:3], v[206:209], v[190:193], v[0:3]
	v_add_u32_e32 v154, 0x18000, v139
	s_barrier
	ds_read_b128 v[142:145], v154
	ds_read_b128 v[146:149], v154 offset:1024
	ds_read_b128 v[150:153], v154 offset:2048
	ds_read_b128 v[154:157], v154 offset:3072
	s_add_u32 s16, s16, 0x40000
	s_addc_u32 s17, s17, 0
	s_mov_b32 m0, s23
	ds_read_b128 v[158:161], v141 offset:32768
	ds_read_b128 v[162:165], v141 offset:33792
	ds_read_b128 v[166:169], v141 offset:34816
	ds_read_b128 v[170:173], v141 offset:35840
	ds_read_b128 v[178:181], v141 offset:36864
	ds_read_b128 v[182:185], v141 offset:37888
	ds_read_b128 v[186:189], v141 offset:38912
	global_load_lds_dwordx4 v132, s[16:17]
	s_mov_b32 m0, s26
	ds_read_b128 v[190:193], v141 offset:39936
	global_load_lds_dwordx4 v130, s[16:17]
	s_waitcnt lgkmcnt(8)
	s_barrier
	s_waitcnt lgkmcnt(0)
	v_mfma_f32_16x16x32_bf16 v[124:127], v[142:145], v[158:161], v[124:127]
	v_mfma_f32_16x16x32_bf16 v[120:123], v[150:153], v[158:161], v[120:123]
	v_mfma_f32_16x16x32_bf16 v[116:119], v[142:145], v[166:169], v[116:119]
	v_mfma_f32_16x16x32_bf16 v[112:115], v[150:153], v[166:169], v[112:115]
	v_mfma_f32_16x16x32_bf16 v[100:103], v[142:145], v[178:181], v[100:103]
	v_mfma_f32_16x16x32_bf16 v[96:99], v[150:153], v[178:181], v[96:99]
	v_mfma_f32_16x16x32_bf16 v[84:87], v[142:145], v[186:189], v[84:87]
	v_mfma_f32_16x16x32_bf16 v[80:83], v[150:153], v[186:189], v[80:83]
	v_mfma_f32_16x16x32_bf16 v[124:127], v[146:149], v[162:165], v[124:127]
	v_mfma_f32_16x16x32_bf16 v[120:123], v[154:157], v[162:165], v[120:123]
	v_mfma_f32_16x16x32_bf16 v[116:119], v[146:149], v[170:173], v[116:119]
	v_mfma_f32_16x16x32_bf16 v[112:115], v[154:157], v[170:173], v[112:115]
	v_mfma_f32_16x16x32_bf16 v[100:103], v[146:149], v[182:185], v[100:103]
	v_mfma_f32_16x16x32_bf16 v[96:99], v[154:157], v[182:185], v[96:99]
	v_mfma_f32_16x16x32_bf16 v[84:87], v[146:149], v[190:193], v[84:87]
	v_mfma_f32_16x16x32_bf16 v[80:83], v[154:157], v[190:193], v[80:83]
	s_barrier
	v_add_u32_e32 v206, 0x1c000, v139
	s_add_i32 m0, s20, 0x18000
	ds_read_b128 v[194:197], v206
	ds_read_b128 v[198:201], v206 offset:1024
	ds_read_b128 v[202:205], v206 offset:2048
	global_load_lds_dwordx4 v176, s[98:99]
	s_add_i32 m0, s20, 0x1a000
	ds_read_b128 v[206:209], v206 offset:3072
	global_load_lds_dwordx4 v128, s[98:99]
	s_barrier
	s_waitcnt lgkmcnt(0)
	v_mfma_f32_16x16x32_bf16 v[108:111], v[194:197], v[158:161], v[108:111]
	v_mfma_f32_16x16x32_bf16 v[104:107], v[202:205], v[158:161], v[104:107]
	v_mfma_f32_16x16x32_bf16 v[92:95], v[194:197], v[166:169], v[92:95]
	v_mfma_f32_16x16x32_bf16 v[88:91], v[202:205], v[166:169], v[88:91]
	v_mfma_f32_16x16x32_bf16 v[76:79], v[194:197], v[178:181], v[76:79]
	v_mfma_f32_16x16x32_bf16 v[72:75], v[202:205], v[178:181], v[72:75]
	v_mfma_f32_16x16x32_bf16 v[68:71], v[194:197], v[186:189], v[68:71]
	v_mfma_f32_16x16x32_bf16 v[64:67], v[202:205], v[186:189], v[64:67]
	v_mfma_f32_16x16x32_bf16 v[108:111], v[198:201], v[162:165], v[108:111]
	v_mfma_f32_16x16x32_bf16 v[104:107], v[206:209], v[162:165], v[104:107]
	v_mfma_f32_16x16x32_bf16 v[92:95], v[198:201], v[170:173], v[92:95]
	v_mfma_f32_16x16x32_bf16 v[88:91], v[206:209], v[170:173], v[88:91]
	v_mfma_f32_16x16x32_bf16 v[76:79], v[198:201], v[182:185], v[76:79]
	v_mfma_f32_16x16x32_bf16 v[72:75], v[206:209], v[182:185], v[72:75]
	v_mfma_f32_16x16x32_bf16 v[68:71], v[198:201], v[190:193], v[68:71]
	v_mfma_f32_16x16x32_bf16 v[64:67], v[206:209], v[190:193], v[64:67]
	s_mov_b32 m0, s28
	s_barrier
	ds_read_b128 v[158:161], v141 offset:49152
	ds_read_b128 v[162:165], v141 offset:50176
	ds_read_b128 v[166:169], v141 offset:51200
	ds_read_b128 v[170:173], v141 offset:52224
	ds_read_b128 v[178:181], v141 offset:53248
	ds_read_b128 v[182:185], v141 offset:54272
	ds_read_b128 v[186:189], v141 offset:55296
	global_load_lds_dwordx4 v132, s[100:101]
	s_mov_b32 m0, s29
	ds_read_b128 v[190:193], v141 offset:56320
	global_load_lds_dwordx4 v130, s[100:101]
	s_barrier
	s_waitcnt lgkmcnt(0)
	v_mfma_f32_16x16x32_bf16 v[60:63], v[142:145], v[158:161], v[60:63]
	v_mfma_f32_16x16x32_bf16 v[56:59], v[150:153], v[158:161], v[56:59]
	v_mfma_f32_16x16x32_bf16 v[52:55], v[142:145], v[166:169], v[52:55]
	v_mfma_f32_16x16x32_bf16 v[48:51], v[150:153], v[166:169], v[48:51]
	v_mfma_f32_16x16x32_bf16 v[36:39], v[142:145], v[178:181], v[36:39]
	v_mfma_f32_16x16x32_bf16 v[32:35], v[150:153], v[178:181], v[32:35]
	v_mfma_f32_16x16x32_bf16 v[20:23], v[142:145], v[186:189], v[20:23]
	v_mfma_f32_16x16x32_bf16 v[16:19], v[150:153], v[186:189], v[16:19]
	v_mfma_f32_16x16x32_bf16 v[60:63], v[146:149], v[162:165], v[60:63]
	v_mfma_f32_16x16x32_bf16 v[56:59], v[154:157], v[162:165], v[56:59]
	v_mfma_f32_16x16x32_bf16 v[52:55], v[146:149], v[170:173], v[52:55]
	v_mfma_f32_16x16x32_bf16 v[48:51], v[154:157], v[170:173], v[48:51]
	v_mfma_f32_16x16x32_bf16 v[36:39], v[146:149], v[182:185], v[36:39]
	v_mfma_f32_16x16x32_bf16 v[32:35], v[154:157], v[182:185], v[32:35]
	v_mfma_f32_16x16x32_bf16 v[20:23], v[146:149], v[190:193], v[20:23]
	v_mfma_f32_16x16x32_bf16 v[16:19], v[154:157], v[190:193], v[16:19]
	s_barrier
; __device__ __forceinline__ unsigned cvtpk(float lo, float hi) { const f32x2 v = (f32x2){lo, hi}; const bf16v2 b = __builtin_convertvector(v, bf16v2); return __builtin_bit_cast(unsigned, b); }
; #define PG8_STAGE(bufoff, gbase, voff) do { _Pragma("unroll") for (int _i = 0; _i < 2; ++_i) \
;         __builtin_amdgcn_global_load_lds((const unsigned*)((const char*)(gbase) + (voff)[_i]), (PG8_LAS unsigned*)(lds + (bufoff) + ldsw + _i * 8192), 16, 0, 0); } while (0)
; #define PG8_MMA(ai, bj, At, Bt) do { __builtin_amdgcn_s_setprio(1); _Pragma("unroll") for (int m = 0; m < 4; ++m) _Pragma("unroll") for (int n = 0; n < 2; ++n) _Pragma("unroll") for (int k = 0; k < 2; ++k) \
;         acc[ai][bj][m][n] = __builtin_amdgcn_mfma_f32_16x16x32_bf16(Bt[n][k], At[m][k], acc[ai][bj][m][n], 0, 0, 0); __builtin_amdgcn_s_setprio(0); } while (0)
; #define PG8_WAIT_V(n) asm volatile("s_waitcnt vmcnt(" #n ")" ::: "memory")
; #define PG8_BAR __builtin_amdgcn_s_barrier()
; template <class Epi, class Sched>
; __device__ __forceinline__ void gemm_phase(PG8_LAS unsigned char* lds, const Gemm g, const Sched& S, const Epi& E) {
;     ...
;             PG8_STAGE(PG8_SB(1, 1), b3 + hstep, voffB);
;             PG8_WAIT_V(6); PG8_BAR; PG8_MMA(1, 1, At, B1); PG8_BAR;
;         }
;         if constexpr (!Epi::AFTER_DRAIN) { E(acc, cur, wr, wc, fr, fq); S.done(cur); }
;     __device__ __forceinline__ void operator()(const f32x4 (&acc)[2][2][4][2], const pg8::Unit& u, int wr, int wc, int fr, int fq) const {
;         const int row0 = u.pm * 256 + wr * 64 + fr, col0 = u.pn * 256 + wc * 32 + 8 * fq;
; #pragma unroll
;         for (int ai = 0; ai < 2; ++ai)
; #pragma unroll
;             for (int m = 0; m < 4; ++m) { bf16_t* rowp = O + (size_t)(row0 + ai * 128 + m * 16) * ldc + col0;
; #pragma unroll
;                 for (int bj = 0; bj < 2; ++bj) { const f32x4 v0 = acc[ai][bj][m][0], v1 = acc[ai][bj][m][1];
;                     u32x4 w; w.x = cvtpk(v0[0], v0[1]); w.y = cvtpk(v0[2], v0[3]); w.z = cvtpk(v1[0], v1[1]); w.w = cvtpk(v1[2], v1[3]);
;                     *(u32x4*)(rowp + bj * 128) = w; } }
	s_add_u32 s14, s14, 0x40080
	s_addc_u32 s15, s15, 0
	s_add_i32 m0, s20, 0x1c000
	s_nop 0
	global_load_lds_dwordx4 v176, s[14:15]
	s_add_i32 m0, s20, 0x1e000
	s_nop 0
	global_load_lds_dwordx4 v128, s[14:15]
	s_waitcnt vmcnt(6)
	s_barrier
	v_mfma_f32_16x16x32_bf16 v[44:47], v[194:197], v[158:161], v[44:47]
	v_mfma_f32_16x16x32_bf16 v[40:43], v[202:205], v[158:161], v[40:43]
	v_mfma_f32_16x16x32_bf16 v[28:31], v[194:197], v[166:169], v[28:31]
	v_mfma_f32_16x16x32_bf16 v[24:27], v[202:205], v[166:169], v[24:27]
	v_mfma_f32_16x16x32_bf16 v[12:15], v[194:197], v[178:181], v[12:15]
	v_mfma_f32_16x16x32_bf16 v[8:11], v[202:205], v[178:181], v[8:11]
	v_mfma_f32_16x16x32_bf16 v[4:7], v[194:197], v[186:189], v[4:7]
	v_mfma_f32_16x16x32_bf16 v[0:3], v[202:205], v[186:189], v[0:3]
	v_mfma_f32_16x16x32_bf16 v[44:47], v[198:201], v[162:165], v[44:47]
	v_mfma_f32_16x16x32_bf16 v[40:43], v[206:209], v[162:165], v[40:43]
	v_mfma_f32_16x16x32_bf16 v[28:31], v[198:201], v[170:173], v[28:31]
	v_mfma_f32_16x16x32_bf16 v[24:27], v[206:209], v[170:173], v[24:27]
	v_mfma_f32_16x16x32_bf16 v[12:15], v[198:201], v[182:185], v[12:15]
	v_mfma_f32_16x16x32_bf16 v[8:11], v[206:209], v[182:185], v[8:11]
	v_mfma_f32_16x16x32_bf16 v[4:7], v[198:201], v[190:193], v[4:7]
	v_mfma_f32_16x16x32_bf16 v[0:3], v[206:209], v[190:193], v[0:3]
	s_add_i32 s45, s45, 2
	s_add_u32 s12, s12, 0x100
	s_addc_u32 s13, s13, 0
	s_add_u32 s43, s43, 0x100
	s_addc_u32 s44, s44, 0
	s_cmp_gt_u32 s45, 13
	s_barrier
	s_cbranch_scc0 .LBB0_137
	v_lshl_add_u32 v142, s0, 8, v138
	v_lshl_or_b32 v144, s34, 8, v140
	v_ashrrev_i32_e32 v143, 31, v142
	v_readlane_b32 s12, v253, 18
	v_ashrrev_i32_e32 v145, 31, v144
	v_lshlrev_b64 v[146:147], 11, v[142:143]
	v_readlane_b32 s13, v253, 19
	v_cvt_pk_bf16_f32 v108, v108, v109
	v_cvt_pk_bf16_f32 v109, v110, v111
	v_cvt_pk_bf16_f32 v110, v104, v105
	v_or_b32_e32 v104, 16, v142
	v_cvt_pk_bf16_f32 v92, v92, v93
	v_cvt_pk_bf16_f32 v93, v94, v95
	v_cvt_pk_bf16_f32 v94, v88, v89
	v_or_b32_e32 v88, 32, v142
	v_cvt_pk_bf16_f32 v76, v76, v77
	v_cvt_pk_bf16_f32 v77, v78, v79
	v_cvt_pk_bf16_f32 v78, v72, v73
	v_or_b32_e32 v72, 48, v142
	v_lshl_add_u64 v[146:147], s[12:13], 0, v[146:147]
	v_lshlrev_b64 v[144:145], 1, v[144:145]
	v_ashrrev_i32_e32 v105, 31, v104
	v_ashrrev_i32_e32 v89, 31, v88
	v_ashrrev_i32_e32 v73, 31, v72
	v_lshl_add_u64 v[146:147], v[146:147], 0, v[144:145]
	v_lshlrev_b64 v[104:105], 11, v[104:105]
	v_lshlrev_b64 v[88:89], 11, v[88:89]
	v_lshlrev_b64 v[72:73], 11, v[72:73]
	v_lshl_add_u64 v[104:105], s[12:13], 0, v[104:105]
	v_lshl_add_u64 v[88:89], s[12:13], 0, v[88:89]
	v_lshl_add_u64 v[72:73], s[12:13], 0, v[72:73]
	s_mov_b64 s[12:13], 0x40000
	v_cvt_pk_bf16_f32 v60, v60, v61
	v_cvt_pk_bf16_f32 v61, v62, v63
	v_cvt_pk_bf16_f32 v62, v56, v57
	v_add_co_u32_e32 v56, vcc, s2, v146
	v_cvt_pk_bf16_f32 v68, v68, v69
	v_cvt_pk_bf16_f32 v69, v70, v71
	v_cvt_pk_bf16_f32 v70, v64, v65
	v_lshl_add_u64 v[64:65], v[146:147], 0, s[12:13]
	v_addc_co_u32_e32 v57, vcc, 0, v147, vcc
	v_cvt_pk_bf16_f32 v44, v44, v45
	v_cvt_pk_bf16_f32 v45, v46, v47
	v_cvt_pk_bf16_f32 v46, v40, v41
	v_cvt_pk_bf16_f32 v47, v42, v43
	s_mov_b32 s0, 0x48000
	global_store_dwordx4 v[64:65], v[44:47], off offset:256
	s_mov_b64 s[12:13], 0x48000
	v_cvt_pk_bf16_f32 v28, v28, v29
	v_add_co_u32_e32 v46, vcc, s0, v146
	v_lshl_add_u64 v[44:45], v[146:147], 0, s[12:13]
	s_nop 0
	v_addc_co_u32_e32 v47, vcc, 0, v147, vcc
	v_cvt_pk_bf16_f32 v29, v30, v31
	v_cvt_pk_bf16_f32 v30, v24, v25
	v_cvt_pk_bf16_f32 v31, v26, v27
	s_mov_b32 s0, 0x50000
	global_store_dwordx4 v[44:45], v[28:31], off offset:256
	s_mov_b64 s[12:13], 0x50000
	v_cvt_pk_bf16_f32 v111, v106, v107
	v_add_co_u32_e32 v30, vcc, s0, v146
	v_lshl_add_u64 v[28:29], v[146:147], 0, s[12:13]
	s_nop 0
	v_addc_co_u32_e32 v31, vcc, 0, v147, vcc
	v_cvt_pk_bf16_f32 v12, v12, v13
	v_cvt_pk_bf16_f32 v13, v14, v15
	v_cvt_pk_bf16_f32 v14, v8, v9
	v_cvt_pk_bf16_f32 v15, v10, v11
	s_mov_b32 s0, 0x58000
	global_store_dwordx4 v[146:147], v[108:111], off offset:256
	v_cvt_pk_bf16_f32 v95, v90, v91
	global_store_dwordx4 v[28:29], v[12:15], off offset:256
	v_lshl_add_u64 v[108:109], v[104:105], 0, v[144:145]
	global_store_dwordx4 v[108:109], v[92:95], off offset:256
	v_add_co_u32_e32 v14, vcc, s0, v146
	s_nop 0
	v_lshl_add_u64 v[92:93], v[88:89], 0, v[144:145]
	v_cvt_pk_bf16_f32 v79, v74, v75
	s_mov_b64 s[12:13], 0x58000
	v_addc_co_u32_e32 v15, vcc, 0, v147, vcc
	v_cvt_pk_bf16_f32 v124, v124, v125
	v_cvt_pk_bf16_f32 v125, v126, v127
	v_cvt_pk_bf16_f32 v126, v120, v121
	v_cvt_pk_bf16_f32 v127, v122, v123
	v_cvt_pk_bf16_f32 v104, v116, v117
	v_cvt_pk_bf16_f32 v105, v118, v119
	v_cvt_pk_bf16_f32 v106, v112, v113
	v_cvt_pk_bf16_f32 v107, v114, v115
	v_cvt_pk_bf16_f32 v88, v100, v101
	v_cvt_pk_bf16_f32 v89, v102, v103
	v_cvt_pk_bf16_f32 v90, v96, v97
	v_cvt_pk_bf16_f32 v91, v98, v99
	global_store_dwordx4 v[92:93], v[76:79], off offset:256
	v_cvt_pk_bf16_f32 v74, v80, v81
	v_cvt_pk_bf16_f32 v75, v82, v83
	v_lshl_add_u64 v[76:77], v[72:73], 0, v[144:145]
	v_cvt_pk_bf16_f32 v72, v84, v85
	v_cvt_pk_bf16_f32 v73, v86, v87
	v_cvt_pk_bf16_f32 v71, v66, v67
	v_cvt_pk_bf16_f32 v63, v58, v59
	v_cvt_pk_bf16_f32 v40, v52, v53
	v_cvt_pk_bf16_f32 v41, v54, v55
	v_cvt_pk_bf16_f32 v42, v48, v49
	v_cvt_pk_bf16_f32 v43, v50, v51
	v_cvt_pk_bf16_f32 v24, v36, v37
	v_cvt_pk_bf16_f32 v25, v38, v39
	v_cvt_pk_bf16_f32 v26, v32, v33
	v_cvt_pk_bf16_f32 v27, v34, v35
	v_lshl_add_u64 v[12:13], v[146:147], 0, s[12:13]
	v_cvt_pk_bf16_f32 v8, v20, v21
	v_cvt_pk_bf16_f32 v9, v22, v23
	v_cvt_pk_bf16_f32 v10, v16, v17
	v_cvt_pk_bf16_f32 v11, v18, v19
	v_cvt_pk_bf16_f32 v4, v4, v5
	v_cvt_pk_bf16_f32 v5, v6, v7
	v_cvt_pk_bf16_f32 v6, v0, v1
	v_cvt_pk_bf16_f32 v7, v2, v3
	s_and_b64 vcc, exec, s[38:39]
	s_mov_b32 s34, s4
	s_mov_b32 s0, s6
	s_mov_b64 s[14:15], s[10:11]
	s_mov_b64 s[12:13], s[8:9]
	global_store_dwordx4 v[146:147], v[124:127], off
	global_store_dwordx4 v[108:109], v[104:107], off
	global_store_dwordx4 v[92:93], v[88:91], off
	global_store_dwordx4 v[76:77], v[72:75], off
	global_store_dwordx4 v[76:77], v[68:71], off offset:256
	global_store_dwordx4 v[56:57], v[60:63], off
	global_store_dwordx4 v[46:47], v[40:43], off
	global_store_dwordx4 v[30:31], v[24:27], off
	global_store_dwordx4 v[14:15], v[8:11], off
	global_store_dwordx4 v[12:13], v[4:7], off offset:256
	s_cbranch_vccz .LBB0_134
	s_waitcnt vmcnt(0)
	v_readlane_b32 s22, v255, 14
	s_cmpk_gt_u32 s19, 0xff
	v_readlane_b32 s23, v255, 15
	s_mov_b64 s[28:29], s[54:55]
	s_cbranch_scc1 .LBB0_141
	s_barrier

; #define PG8_STAGE(bufoff, gbase, voff) do { _Pragma("unroll") for (int _i = 0; _i < 2; ++_i) \
;         __builtin_amdgcn_global_load_lds((const unsigned*)((const char*)(gbase) + (voff)[_i]), (PG8_LAS unsigned*)(lds + (bufoff) + ldsw + _i * 8192), 16, 0, 0); } while (0)
; #define PG8_LDA(dst, b, h) do { _Pragma("unroll") for (int m = 0; m < 4; ++m) _Pragma("unroll") for (int k = 0; k < 2; ++k) dst[m][k] = *(const PG8_LAS bf16x8*)(lds + PG8_SA(b, h) + aoff + m * 2048 + k * 1024); } while (0)
; #define PG8_LDB(dst, b, h) do { _Pragma("unroll") for (int n = 0; n < 2; ++n) _Pragma("unroll") for (int k = 0; k < 2; ++k) dst[n][k] = *(const PG8_LAS bf16x8*)(lds + PG8_SB(b, h) + boff + n * 2048 + k * 1024); } while (0)
; #define PG8_MMA(ai, bj, At, Bt) do { __builtin_amdgcn_s_setprio(1); _Pragma("unroll") for (int m = 0; m < 4; ++m) _Pragma("unroll") for (int n = 0; n < 2; ++n) _Pragma("unroll") for (int k = 0; k < 2; ++k) \
;         acc[ai][bj][m][n] = __builtin_amdgcn_mfma_f32_16x16x32_bf16(Bt[n][k], At[m][k], acc[ai][bj][m][n], 0, 0, 0); __builtin_amdgcn_s_setprio(0); } while (0)
; #define PG8_WAIT_V(n) asm volatile("s_waitcnt vmcnt(" #n ")" ::: "memory")
; template <class Epi, class Sched>
; __device__ __forceinline__ void gemm_phase(PG8_LAS unsigned char* lds, const Gemm g, const Sched& S, const Epi& E) {
;     ...
;         for (int t = 0; t < nt; t += 2) {
;             const bool last = (t == nt - 2);
;             const char* a1 = cA + (size_t)(t + 1) * kstep;
;             const char* a2 = last ? nA : cA + (size_t)(t + 2) * kstep; const char* b2 = last ? nB : cB + (size_t)(t + 2) * kstep;
;             const char* a3 = a2 + kstep; const char* b3 = b2 + kstep;
;             if (last && has_next) S.a_ready(nxt);
;             PG8_LDB(B0, 0, 0); PG8_SCHED; PG8_LDA(At, 0, 0); PG8_STAGE(PG8_SA(1, 1), a1 + hstep, voffA);
;             PG8_WAIT_L(8); PG8_BAR; PG8_WAIT_L(0); PG8_MMA(0, 0, At, B0); PG8_BAR; PG8_SCHED;
;             PG8_LDB(B1, 0, 1); PG8_STAGE(PG8_SB(0, 0), b2, voffB);
;             PG8_BAR; PG8_WAIT_L(0); PG8_MMA(0, 1, At, B1); PG8_BAR;
;             PG8_LDA(At, 0, 1); PG8_STAGE(PG8_SA(0, 0), a2, voffA);
;             PG8_BAR; PG8_WAIT_L(0); PG8_MMA(1, 0, At, B0); PG8_BAR; PG8_SCHED;
;             PG8_STAGE(PG8_SB(0, 1), b2 + hstep, voffB);
;             PG8_WAIT_V(6); PG8_BAR; PG8_MMA(1, 1, At, B1); PG8_BAR;
.LBB0_358:
	s_add_u32 s14, s12, 0xfffc0080
	s_addc_u32 s15, s13, -1
	v_add_u32_e32 v154, 0x10000, v139
	ds_read_b128 v[142:145], v154
	ds_read_b128 v[146:149], v154 offset:1024
	ds_read_b128 v[150:153], v154 offset:2048
	ds_read_b128 v[154:157], v154 offset:3072
	s_cmp_eq_u32 s45, 12
	s_cselect_b32 s17, s7, s15
	s_cselect_b32 s16, s40, s14
	s_cselect_b32 s15, s5, s44
	s_cselect_b32 s14, s41, s43
	s_add_i32 m0, s1, 0xc000
	ds_read_b128 v[158:161], v141
	ds_read_b128 v[162:165], v141 offset:1024
	ds_read_b128 v[166:169], v141 offset:2048
	ds_read_b128 v[170:173], v141 offset:3072
	ds_read_b128 v[182:185], v141 offset:4096
	ds_read_b128 v[190:193], v141 offset:5120
	ds_read_b128 v[194:197], v141 offset:6144
	global_load_lds_dwordx4 v134, s[12:13]
	s_add_i32 m0, s1, 0xe000
	ds_read_b128 v[198:201], v141 offset:7168
	global_load_lds_dwordx4 v136, s[12:13]
	s_waitcnt lgkmcnt(8)
	s_barrier
	s_waitcnt lgkmcnt(0)
	v_mfma_f32_16x16x32_bf16 v[124:127], v[142:145], v[158:161], v[124:127]
	v_mfma_f32_16x16x32_bf16 v[120:123], v[150:153], v[158:161], v[120:123]
	v_mfma_f32_16x16x32_bf16 v[116:119], v[142:145], v[166:169], v[116:119]
	v_mfma_f32_16x16x32_bf16 v[112:115], v[150:153], v[166:169], v[112:115]
	v_mfma_f32_16x16x32_bf16 v[100:103], v[142:145], v[182:185], v[100:103]
	v_mfma_f32_16x16x32_bf16 v[96:99], v[150:153], v[182:185], v[96:99]
	v_mfma_f32_16x16x32_bf16 v[84:87], v[142:145], v[194:197], v[84:87]
	v_mfma_f32_16x16x32_bf16 v[80:83], v[150:153], v[194:197], v[80:83]
	v_mfma_f32_16x16x32_bf16 v[124:127], v[146:149], v[162:165], v[124:127]
	v_mfma_f32_16x16x32_bf16 v[120:123], v[154:157], v[162:165], v[120:123]
	v_mfma_f32_16x16x32_bf16 v[116:119], v[146:149], v[170:173], v[116:119]
	v_mfma_f32_16x16x32_bf16 v[112:115], v[154:157], v[170:173], v[112:115]
	v_mfma_f32_16x16x32_bf16 v[100:103], v[146:149], v[190:193], v[100:103]
	v_mfma_f32_16x16x32_bf16 v[96:99], v[154:157], v[190:193], v[96:99]
	v_mfma_f32_16x16x32_bf16 v[84:87], v[146:149], v[198:201], v[84:87]
	v_mfma_f32_16x16x32_bf16 v[80:83], v[154:157], v[198:201], v[80:83]
	s_barrier
	s_add_i32 s48, 0, 0x14000
	v_add_u32_e32 v174, 0x14000, v139
	ds_read_b128 v[202:205], v174
	ds_read_b128 v[206:209], v174 offset:1024
	s_add_u32 s98, s14, 0x80
	s_addc_u32 s99, s15, 0
	s_add_i32 m0, s20, 0x10000
	ds_read_b128 v[210:213], v174 offset:2048
	global_load_lds_dwordx4 v176, s[14:15]
	s_add_i32 m0, s20, 0x12000
	ds_read_b128 v[214:217], v174 offset:3072
	global_load_lds_dwordx4 v128, s[14:15]
	s_barrier
	s_waitcnt lgkmcnt(0)
	v_mfma_f32_16x16x32_bf16 v[108:111], v[202:205], v[158:161], v[108:111]
	v_mfma_f32_16x16x32_bf16 v[104:107], v[210:213], v[158:161], v[104:107]
	v_mfma_f32_16x16x32_bf16 v[92:95], v[202:205], v[166:169], v[92:95]
	v_mfma_f32_16x16x32_bf16 v[88:91], v[210:213], v[166:169], v[88:91]
	v_mfma_f32_16x16x32_bf16 v[76:79], v[202:205], v[182:185], v[76:79]
	v_mfma_f32_16x16x32_bf16 v[72:75], v[210:213], v[182:185], v[72:75]
	v_mfma_f32_16x16x32_bf16 v[68:71], v[202:205], v[194:197], v[68:71]
	v_mfma_f32_16x16x32_bf16 v[64:67], v[210:213], v[194:197], v[64:67]
	v_mfma_f32_16x16x32_bf16 v[108:111], v[206:209], v[162:165], v[108:111]
	v_mfma_f32_16x16x32_bf16 v[104:107], v[214:217], v[162:165], v[104:107]
	v_mfma_f32_16x16x32_bf16 v[92:95], v[206:209], v[170:173], v[92:95]
	v_mfma_f32_16x16x32_bf16 v[88:91], v[214:217], v[170:173], v[88:91]
	v_mfma_f32_16x16x32_bf16 v[76:79], v[206:209], v[190:193], v[76:79]
	v_mfma_f32_16x16x32_bf16 v[72:75], v[214:217], v[190:193], v[72:75]
	v_mfma_f32_16x16x32_bf16 v[68:71], v[206:209], v[198:201], v[68:71]
	v_mfma_f32_16x16x32_bf16 v[64:67], v[214:217], v[198:201], v[64:67]
	s_mov_b32 m0, s1
	s_add_u32 s100, s16, 0x80
	s_addc_u32 s101, s17, 0
	s_barrier
	ds_read_b128 v[158:161], v141 offset:16384
	ds_read_b128 v[162:165], v141 offset:17408
	ds_read_b128 v[166:169], v141 offset:18432
	ds_read_b128 v[170:173], v141 offset:19456
	ds_read_b128 v[182:185], v141 offset:20480
	ds_read_b128 v[190:193], v141 offset:21504
	ds_read_b128 v[194:197], v141 offset:22528
	global_load_lds_dwordx4 v132, s[16:17]
	s_mov_b32 m0, s22
	ds_read_b128 v[198:201], v141 offset:23552
	global_load_lds_dwordx4 v130, s[16:17]
	s_barrier
	s_waitcnt lgkmcnt(0)
	v_mfma_f32_16x16x32_bf16 v[60:63], v[142:145], v[158:161], v[60:63]
	v_mfma_f32_16x16x32_bf16 v[56:59], v[150:153], v[158:161], v[56:59]
	v_mfma_f32_16x16x32_bf16 v[52:55], v[142:145], v[166:169], v[52:55]
	v_mfma_f32_16x16x32_bf16 v[48:51], v[150:153], v[166:169], v[48:51]
	v_mfma_f32_16x16x32_bf16 v[36:39], v[142:145], v[182:185], v[36:39]
	v_mfma_f32_16x16x32_bf16 v[32:35], v[150:153], v[182:185], v[32:35]
	v_mfma_f32_16x16x32_bf16 v[20:23], v[142:145], v[194:197], v[20:23]
	v_mfma_f32_16x16x32_bf16 v[16:19], v[150:153], v[194:197], v[16:19]
	v_mfma_f32_16x16x32_bf16 v[60:63], v[146:149], v[162:165], v[60:63]
	v_mfma_f32_16x16x32_bf16 v[56:59], v[154:157], v[162:165], v[56:59]
	v_mfma_f32_16x16x32_bf16 v[52:55], v[146:149], v[170:173], v[52:55]
	v_mfma_f32_16x16x32_bf16 v[48:51], v[154:157], v[170:173], v[48:51]
	v_mfma_f32_16x16x32_bf16 v[36:39], v[146:149], v[190:193], v[36:39]
	v_mfma_f32_16x16x32_bf16 v[32:35], v[154:157], v[190:193], v[32:35]
	v_mfma_f32_16x16x32_bf16 v[20:23], v[146:149], v[198:201], v[20:23]
	v_mfma_f32_16x16x32_bf16 v[16:19], v[154:157], v[198:201], v[16:19]
	s_barrier
	s_add_u32 s46, s14, 0x40000
	s_addc_u32 s47, s15, 0
	s_add_i32 m0, s20, 0x14000
	s_nop 0
	global_load_lds_dwordx4 v176, s[46:47]
	s_add_i32 m0, s20, 0x16000
	s_nop 0
	global_load_lds_dwordx4 v128, s[46:47]
	s_waitcnt vmcnt(6)
	s_barrier
; #define PG8_STAGE(bufoff, gbase, voff) do { _Pragma("unroll") for (int _i = 0; _i < 2; ++_i) \
;         __builtin_amdgcn_global_load_lds((const unsigned*)((const char*)(gbase) + (voff)[_i]), (PG8_LAS unsigned*)(lds + (bufoff) + ldsw + _i * 8192), 16, 0, 0); } while (0)
; #define PG8_LDA(dst, b, h) do { _Pragma("unroll") for (int m = 0; m < 4; ++m) _Pragma("unroll") for (int k = 0; k < 2; ++k) dst[m][k] = *(const PG8_LAS bf16x8*)(lds + PG8_SA(b, h) + aoff + m * 2048 + k * 1024); } while (0)
; #define PG8_LDB(dst, b, h) do { _Pragma("unroll") for (int n = 0; n < 2; ++n) _Pragma("unroll") for (int k = 0; k < 2; ++k) dst[n][k] = *(const PG8_LAS bf16x8*)(lds + PG8_SB(b, h) + boff + n * 2048 + k * 1024); } while (0)
; #define PG8_MMA(ai, bj, At, Bt) do { __builtin_amdgcn_s_setprio(1); _Pragma("unroll") for (int m = 0; m < 4; ++m) _Pragma("unroll") for (int n = 0; n < 2; ++n) _Pragma("unroll") for (int k = 0; k < 2; ++k) \
;         acc[ai][bj][m][n] = __builtin_amdgcn_mfma_f32_16x16x32_bf16(Bt[n][k], At[m][k], acc[ai][bj][m][n], 0, 0, 0); __builtin_amdgcn_s_setprio(0); } while (0)
; #define PG8_WAIT_V(n) asm volatile("s_waitcnt vmcnt(" #n ")" ::: "memory")
; #define PG8_WAIT_L(n) asm volatile("s_waitcnt lgkmcnt(" #n ")" ::: "memory")
; #define PG8_BAR __builtin_amdgcn_s_barrier()
; #define PG8_SCHED __builtin_amdgcn_sched_barrier(0)
; template <class Epi, class Sched>
; __device__ __forceinline__ void gemm_phase(PG8_LAS unsigned char* lds, const Gemm g, const Sched& S, const Epi& E) {
;     ...
;             PG8_WAIT_V(6); PG8_BAR; PG8_MMA(1, 1, At, B1); PG8_BAR;
;             PG8_LDB(B0, 1, 0); PG8_SCHED; PG8_LDA(At, 1, 0); PG8_STAGE(PG8_SA(0, 1), a2 + hstep, voffA);
;             PG8_WAIT_L(8); PG8_BAR; PG8_WAIT_L(0); PG8_MMA(0, 0, At, B0); PG8_BAR; PG8_SCHED;
;             PG8_LDB(B1, 1, 1); PG8_STAGE(PG8_SB(1, 0), b3, voffB);
;             PG8_BAR; PG8_WAIT_L(0); PG8_MMA(0, 1, At, B1); PG8_BAR;
;             PG8_LDA(At, 1, 1); PG8_STAGE(PG8_SA(1, 0), a3, voffA);
;             PG8_BAR; PG8_WAIT_L(0); PG8_MMA(1, 0, At, B0); PG8_BAR; PG8_SCHED;
	v_mfma_f32_16x16x32_bf16 v[44:47], v[202:205], v[158:161], v[44:47]
	v_mfma_f32_16x16x32_bf16 v[40:43], v[210:213], v[158:161], v[40:43]
	v_mfma_f32_16x16x32_bf16 v[28:31], v[202:205], v[166:169], v[28:31]
	v_mfma_f32_16x16x32_bf16 v[24:27], v[210:213], v[166:169], v[24:27]
	v_mfma_f32_16x16x32_bf16 v[12:15], v[202:205], v[182:185], v[12:15]
	v_mfma_f32_16x16x32_bf16 v[8:11], v[210:213], v[182:185], v[8:11]
	v_mfma_f32_16x16x32_bf16 v[4:7], v[202:205], v[194:197], v[4:7]
	v_mfma_f32_16x16x32_bf16 v[0:3], v[210:213], v[194:197], v[0:3]
	v_mfma_f32_16x16x32_bf16 v[44:47], v[206:209], v[162:165], v[44:47]
	v_mfma_f32_16x16x32_bf16 v[40:43], v[214:217], v[162:165], v[40:43]
	v_mfma_f32_16x16x32_bf16 v[28:31], v[206:209], v[170:173], v[28:31]
	v_mfma_f32_16x16x32_bf16 v[24:27], v[214:217], v[170:173], v[24:27]
	v_mfma_f32_16x16x32_bf16 v[12:15], v[206:209], v[190:193], v[12:15]
	v_mfma_f32_16x16x32_bf16 v[8:11], v[214:217], v[190:193], v[8:11]
	v_mfma_f32_16x16x32_bf16 v[4:7], v[206:209], v[198:201], v[4:7]
	v_mfma_f32_16x16x32_bf16 v[0:3], v[214:217], v[198:201], v[0:3]
	v_add_u32_e32 v154, 0x18000, v139
	s_barrier
	ds_read_b128 v[142:145], v154
	ds_read_b128 v[146:149], v154 offset:1024
	ds_read_b128 v[150:153], v154 offset:2048
	ds_read_b128 v[154:157], v154 offset:3072
	s_add_u32 s16, s16, 0x40000
	s_addc_u32 s17, s17, 0
	s_mov_b32 m0, s23
	ds_read_b128 v[158:161], v141 offset:32768
	ds_read_b128 v[162:165], v141 offset:33792
	ds_read_b128 v[166:169], v141 offset:34816
	ds_read_b128 v[170:173], v141 offset:35840
	ds_read_b128 v[182:185], v141 offset:36864
	ds_read_b128 v[190:193], v141 offset:37888
	ds_read_b128 v[194:197], v141 offset:38912
	global_load_lds_dwordx4 v132, s[16:17]
	s_mov_b32 m0, s26
	ds_read_b128 v[198:201], v141 offset:39936
	global_load_lds_dwordx4 v130, s[16:17]
	s_waitcnt lgkmcnt(8)
	s_barrier
	s_waitcnt lgkmcnt(0)
	v_mfma_f32_16x16x32_bf16 v[124:127], v[142:145], v[158:161], v[124:127]
	v_mfma_f32_16x16x32_bf16 v[120:123], v[150:153], v[158:161], v[120:123]
	v_mfma_f32_16x16x32_bf16 v[116:119], v[142:145], v[166:169], v[116:119]
	v_mfma_f32_16x16x32_bf16 v[112:115], v[150:153], v[166:169], v[112:115]
	v_mfma_f32_16x16x32_bf16 v[100:103], v[142:145], v[182:185], v[100:103]
	v_mfma_f32_16x16x32_bf16 v[96:99], v[150:153], v[182:185], v[96:99]
	v_mfma_f32_16x16x32_bf16 v[84:87], v[142:145], v[194:197], v[84:87]
	v_mfma_f32_16x16x32_bf16 v[80:83], v[150:153], v[194:197], v[80:83]
	v_mfma_f32_16x16x32_bf16 v[124:127], v[146:149], v[162:165], v[124:127]
	v_mfma_f32_16x16x32_bf16 v[120:123], v[154:157], v[162:165], v[120:123]
	v_mfma_f32_16x16x32_bf16 v[116:119], v[146:149], v[170:173], v[116:119]
	v_mfma_f32_16x16x32_bf16 v[112:115], v[154:157], v[170:173], v[112:115]
	v_mfma_f32_16x16x32_bf16 v[100:103], v[146:149], v[190:193], v[100:103]
	v_mfma_f32_16x16x32_bf16 v[96:99], v[154:157], v[190:193], v[96:99]
	v_mfma_f32_16x16x32_bf16 v[84:87], v[146:149], v[198:201], v[84:87]
	v_mfma_f32_16x16x32_bf16 v[80:83], v[154:157], v[198:201], v[80:83]
	s_barrier
	v_add_u32_e32 v188, 0x1c000, v139
	s_add_i32 m0, s20, 0x18000
	ds_read_b128 v[202:205], v188
	ds_read_b128 v[206:209], v188 offset:1024
	ds_read_b128 v[210:213], v188 offset:2048
	global_load_lds_dwordx4 v176, s[98:99]
	s_add_i32 m0, s20, 0x1a000
	ds_read_b128 v[214:217], v188 offset:3072
	global_load_lds_dwordx4 v128, s[98:99]
	s_barrier
	s_waitcnt lgkmcnt(0)
	v_mfma_f32_16x16x32_bf16 v[108:111], v[202:205], v[158:161], v[108:111]
	v_mfma_f32_16x16x32_bf16 v[104:107], v[210:213], v[158:161], v[104:107]
	v_mfma_f32_16x16x32_bf16 v[92:95], v[202:205], v[166:169], v[92:95]
	v_mfma_f32_16x16x32_bf16 v[88:91], v[210:213], v[166:169], v[88:91]
	v_mfma_f32_16x16x32_bf16 v[76:79], v[202:205], v[182:185], v[76:79]
	v_mfma_f32_16x16x32_bf16 v[72:75], v[210:213], v[182:185], v[72:75]
	v_mfma_f32_16x16x32_bf16 v[68:71], v[202:205], v[194:197], v[68:71]
	v_mfma_f32_16x16x32_bf16 v[64:67], v[210:213], v[194:197], v[64:67]
	v_mfma_f32_16x16x32_bf16 v[108:111], v[206:209], v[162:165], v[108:111]
	v_mfma_f32_16x16x32_bf16 v[104:107], v[214:217], v[162:165], v[104:107]
	v_mfma_f32_16x16x32_bf16 v[92:95], v[206:209], v[170:173], v[92:95]
	v_mfma_f32_16x16x32_bf16 v[88:91], v[214:217], v[170:173], v[88:91]
	v_mfma_f32_16x16x32_bf16 v[76:79], v[206:209], v[190:193], v[76:79]
	v_mfma_f32_16x16x32_bf16 v[72:75], v[214:217], v[190:193], v[72:75]
	v_mfma_f32_16x16x32_bf16 v[68:71], v[206:209], v[198:201], v[68:71]
	v_mfma_f32_16x16x32_bf16 v[64:67], v[214:217], v[198:201], v[64:67]
	s_mov_b32 m0, s28
	s_barrier
	ds_read_b128 v[158:161], v141 offset:49152
	ds_read_b128 v[162:165], v141 offset:50176
	ds_read_b128 v[166:169], v141 offset:51200
	ds_read_b128 v[170:173], v141 offset:52224
	ds_read_b128 v[182:185], v141 offset:53248
	ds_read_b128 v[190:193], v141 offset:54272
	ds_read_b128 v[194:197], v141 offset:55296
	global_load_lds_dwordx4 v132, s[100:101]
	s_mov_b32 m0, s29
	ds_read_b128 v[198:201], v141 offset:56320
	global_load_lds_dwordx4 v130, s[100:101]
	s_barrier
	s_waitcnt lgkmcnt(0)
	v_mfma_f32_16x16x32_bf16 v[60:63], v[142:145], v[158:161], v[60:63]
	v_mfma_f32_16x16x32_bf16 v[56:59], v[150:153], v[158:161], v[56:59]
	v_mfma_f32_16x16x32_bf16 v[52:55], v[142:145], v[166:169], v[52:55]
	v_mfma_f32_16x16x32_bf16 v[48:51], v[150:153], v[166:169], v[48:51]
	v_mfma_f32_16x16x32_bf16 v[36:39], v[142:145], v[182:185], v[36:39]
	v_mfma_f32_16x16x32_bf16 v[32:35], v[150:153], v[182:185], v[32:35]
	v_mfma_f32_16x16x32_bf16 v[20:23], v[142:145], v[194:197], v[20:23]
	v_mfma_f32_16x16x32_bf16 v[16:19], v[150:153], v[194:197], v[16:19]
	v_mfma_f32_16x16x32_bf16 v[60:63], v[146:149], v[162:165], v[60:63]
	v_mfma_f32_16x16x32_bf16 v[56:59], v[154:157], v[162:165], v[56:59]
	v_mfma_f32_16x16x32_bf16 v[52:55], v[146:149], v[170:173], v[52:55]
	v_mfma_f32_16x16x32_bf16 v[48:51], v[154:157], v[170:173], v[48:51]
	v_mfma_f32_16x16x32_bf16 v[36:39], v[146:149], v[190:193], v[36:39]
	v_mfma_f32_16x16x32_bf16 v[32:35], v[154:157], v[190:193], v[32:35]
	v_mfma_f32_16x16x32_bf16 v[20:23], v[146:149], v[198:201], v[20:23]
	v_mfma_f32_16x16x32_bf16 v[16:19], v[154:157], v[198:201], v[16:19]
	s_barrier
; __device__ __forceinline__ unsigned cvtpk(float lo, float hi) { const f32x2 v = (f32x2){lo, hi}; const bf16v2 b = __builtin_convertvector(v, bf16v2); return __builtin_bit_cast(unsigned, b); }
; #define PG8_STAGE(bufoff, gbase, voff) do { _Pragma("unroll") for (int _i = 0; _i < 2; ++_i) \
;         __builtin_amdgcn_global_load_lds((const unsigned*)((const char*)(gbase) + (voff)[_i]), (PG8_LAS unsigned*)(lds + (bufoff) + ldsw + _i * 8192), 16, 0, 0); } while (0)
; #define PG8_MMA(ai, bj, At, Bt) do { __builtin_amdgcn_s_setprio(1); _Pragma("unroll") for (int m = 0; m < 4; ++m) _Pragma("unroll") for (int n = 0; n < 2; ++n) _Pragma("unroll") for (int k = 0; k < 2; ++k) \
;         acc[ai][bj][m][n] = __builtin_amdgcn_mfma_f32_16x16x32_bf16(Bt[n][k], At[m][k], acc[ai][bj][m][n], 0, 0, 0); __builtin_amdgcn_s_setprio(0); } while (0)
; #define PG8_WAIT_V(n) asm volatile("s_waitcnt vmcnt(" #n ")" ::: "memory")
; #define PG8_BAR __builtin_amdgcn_s_barrier()
; template <class Epi, class Sched>
; __device__ __forceinline__ void gemm_phase(PG8_LAS unsigned char* lds, const Gemm g, const Sched& S, const Epi& E) {
;     ...
;             PG8_STAGE(PG8_SB(1, 1), b3 + hstep, voffB);
;             PG8_WAIT_V(6); PG8_BAR; PG8_MMA(1, 1, At, B1); PG8_BAR;
;         }
;         if constexpr (!Epi::AFTER_DRAIN) { E(acc, cur, wr, wc, fr, fq); S.done(cur); }
;     __device__ __forceinline__ void operator()(const f32x4 (&acc)[2][2][4][2], const pg8::Unit& u, int wr, int wc, int fr, int fq) const {
;         const int row0 = u.pm * 256 + wr * 64 + fr, col0 = u.pn * 256 + wc * 32 + 8 * fq;
; #pragma unroll
;         for (int ai = 0; ai < 2; ++ai)
; #pragma unroll
;             for (int m = 0; m < 4; ++m) { bf16_t* rowp = O + (size_t)(row0 + ai * 128 + m * 16) * ldc + col0;
; #pragma unroll
;                 for (int bj = 0; bj < 2; ++bj) { const f32x4 v0 = acc[ai][bj][m][0], v1 = acc[ai][bj][m][1];
;                     u32x4 w; w.x = cvtpk(v0[0], v0[1]); w.y = cvtpk(v0[2], v0[3]); w.z = cvtpk(v1[0], v1[1]); w.w = cvtpk(v1[2], v1[3]);
;                     *(u32x4*)(rowp + bj * 128) = w; } }
	s_add_u32 s14, s14, 0x40080
	s_addc_u32 s15, s15, 0
	s_add_i32 m0, s20, 0x1c000
	s_nop 0
	global_load_lds_dwordx4 v176, s[14:15]
	s_add_i32 m0, s20, 0x1e000
	s_nop 0
	global_load_lds_dwordx4 v128, s[14:15]
	s_waitcnt vmcnt(6)
	s_barrier
	v_mfma_f32_16x16x32_bf16 v[44:47], v[202:205], v[158:161], v[44:47]
	v_mfma_f32_16x16x32_bf16 v[40:43], v[210:213], v[158:161], v[40:43]
	v_mfma_f32_16x16x32_bf16 v[28:31], v[202:205], v[166:169], v[28:31]
	v_mfma_f32_16x16x32_bf16 v[24:27], v[210:213], v[166:169], v[24:27]
	v_mfma_f32_16x16x32_bf16 v[12:15], v[202:205], v[182:185], v[12:15]
	v_mfma_f32_16x16x32_bf16 v[8:11], v[210:213], v[182:185], v[8:11]
	v_mfma_f32_16x16x32_bf16 v[4:7], v[202:205], v[194:197], v[4:7]
	v_mfma_f32_16x16x32_bf16 v[0:3], v[210:213], v[194:197], v[0:3]
	v_mfma_f32_16x16x32_bf16 v[44:47], v[206:209], v[162:165], v[44:47]
	v_mfma_f32_16x16x32_bf16 v[40:43], v[214:217], v[162:165], v[40:43]
	v_mfma_f32_16x16x32_bf16 v[28:31], v[206:209], v[170:173], v[28:31]
	v_mfma_f32_16x16x32_bf16 v[24:27], v[214:217], v[170:173], v[24:27]
	v_mfma_f32_16x16x32_bf16 v[12:15], v[206:209], v[190:193], v[12:15]
	v_mfma_f32_16x16x32_bf16 v[8:11], v[214:217], v[190:193], v[8:11]
	v_mfma_f32_16x16x32_bf16 v[4:7], v[206:209], v[198:201], v[4:7]
	v_mfma_f32_16x16x32_bf16 v[0:3], v[214:217], v[198:201], v[0:3]
	s_add_i32 s45, s45, 2
	s_add_u32 s12, s12, 0x100
	s_addc_u32 s13, s13, 0
	s_add_u32 s43, s43, 0x100
	s_addc_u32 s44, s44, 0
	s_cmp_gt_u32 s45, 13
	s_barrier
	s_cbranch_scc0 .LBB0_358
	v_readlane_b32 s12, v253, 16
	v_lshl_add_u32 v148, s0, 8, v138
	v_lshl_or_b32 v142, s34, 8, v140
	v_readlane_b32 s13, v253, 17
	v_ashrrev_i32_e32 v143, 31, v142
	v_cvt_pk_bf16_f32 v68, v68, v69
	v_mov_b64_e32 v[144:145], s[12:13]
	v_cvt_pk_bf16_f32 v69, v70, v71
	v_cvt_pk_bf16_f32 v70, v64, v65
	v_add_u32_e32 v64, 0x80, v148
	v_mad_i64_i32 v[146:147], s[12:13], v148, s81, v[144:145]
	v_lshlrev_b64 v[142:143], 1, v[142:143]
	v_cvt_pk_bf16_f32 v108, v108, v109
	v_cvt_pk_bf16_f32 v109, v110, v111
	v_cvt_pk_bf16_f32 v110, v104, v105
	v_or_b32_e32 v104, 16, v148
	v_mad_i64_i32 v[64:65], s[12:13], v64, s81, v[144:145]
	v_cvt_pk_bf16_f32 v44, v44, v45
	v_cvt_pk_bf16_f32 v45, v46, v47
	v_cvt_pk_bf16_f32 v46, v40, v41
	v_add_u32_e32 v40, 0x90, v148
	v_lshl_add_u64 v[146:147], v[146:147], 0, v[142:143]
	v_cvt_pk_bf16_f32 v111, v106, v107
	v_mad_i64_i32 v[104:105], s[12:13], v104, s81, v[144:145]
	v_cvt_pk_bf16_f32 v92, v92, v93
	v_cvt_pk_bf16_f32 v93, v94, v95
	v_cvt_pk_bf16_f32 v94, v88, v89
	v_or_b32_e32 v88, 32, v148
	v_lshl_add_u64 v[64:65], v[64:65], 0, v[142:143]
	v_cvt_pk_bf16_f32 v47, v42, v43
	v_mad_i64_i32 v[40:41], s[12:13], v40, s81, v[144:145]
	v_cvt_pk_bf16_f32 v28, v28, v29
	v_cvt_pk_bf16_f32 v29, v30, v31
	v_cvt_pk_bf16_f32 v30, v24, v25
	v_add_u32_e32 v24, 0xa0, v148
	global_store_dwordx4 v[146:147], v[108:111], off offset:256
	v_cvt_pk_bf16_f32 v95, v90, v91
	v_mad_i64_i32 v[88:89], s[12:13], v88, s81, v[144:145]
	v_lshl_add_u64 v[108:109], v[104:105], 0, v[142:143]
	v_cvt_pk_bf16_f32 v76, v76, v77
	v_cvt_pk_bf16_f32 v77, v78, v79
	v_cvt_pk_bf16_f32 v78, v72, v73
	v_or_b32_e32 v72, 48, v148
	global_store_dwordx4 v[64:65], v[44:47], off offset:256
	v_cvt_pk_bf16_f32 v31, v26, v27
	v_mad_i64_i32 v[24:25], s[12:13], v24, s81, v[144:145]
	v_lshl_add_u64 v[44:45], v[40:41], 0, v[142:143]
	v_cvt_pk_bf16_f32 v12, v12, v13
	v_cvt_pk_bf16_f32 v13, v14, v15
	v_cvt_pk_bf16_f32 v14, v8, v9
	v_add_u32_e32 v8, 0xb0, v148
	global_store_dwordx4 v[108:109], v[92:95], off offset:256
	v_cvt_pk_bf16_f32 v79, v74, v75
	v_mad_i64_i32 v[72:73], s[12:13], v72, s81, v[144:145]
	v_lshl_add_u64 v[92:93], v[88:89], 0, v[142:143]
	global_store_dwordx4 v[44:45], v[28:31], off offset:256
	v_cvt_pk_bf16_f32 v15, v10, v11
	v_mad_i64_i32 v[8:9], s[12:13], v8, s81, v[144:145]
	v_lshl_add_u64 v[28:29], v[24:25], 0, v[142:143]
	v_cvt_pk_bf16_f32 v124, v124, v125
	v_cvt_pk_bf16_f32 v125, v126, v127
	v_cvt_pk_bf16_f32 v126, v120, v121
	v_cvt_pk_bf16_f32 v127, v122, v123
	v_cvt_pk_bf16_f32 v104, v116, v117
	v_cvt_pk_bf16_f32 v105, v118, v119
	v_cvt_pk_bf16_f32 v106, v112, v113
	v_cvt_pk_bf16_f32 v107, v114, v115
	v_cvt_pk_bf16_f32 v88, v100, v101
	v_cvt_pk_bf16_f32 v89, v102, v103
	v_cvt_pk_bf16_f32 v90, v96, v97
	v_cvt_pk_bf16_f32 v91, v98, v99
	global_store_dwordx4 v[92:93], v[76:79], off offset:256
	v_cvt_pk_bf16_f32 v74, v80, v81
	v_cvt_pk_bf16_f32 v75, v82, v83
	v_lshl_add_u64 v[76:77], v[72:73], 0, v[142:143]
	v_cvt_pk_bf16_f32 v72, v84, v85
	v_cvt_pk_bf16_f32 v73, v86, v87
	v_cvt_pk_bf16_f32 v71, v66, v67
	v_cvt_pk_bf16_f32 v60, v60, v61
	v_cvt_pk_bf16_f32 v61, v62, v63
	v_cvt_pk_bf16_f32 v62, v56, v57
	v_cvt_pk_bf16_f32 v63, v58, v59
	v_cvt_pk_bf16_f32 v40, v52, v53
	v_cvt_pk_bf16_f32 v41, v54, v55
	v_cvt_pk_bf16_f32 v42, v48, v49
	v_cvt_pk_bf16_f32 v43, v50, v51
	v_cvt_pk_bf16_f32 v24, v36, v37
	v_cvt_pk_bf16_f32 v25, v38, v39
	v_cvt_pk_bf16_f32 v26, v32, v33
	v_cvt_pk_bf16_f32 v27, v34, v35
	global_store_dwordx4 v[28:29], v[12:15], off offset:256
	v_cvt_pk_bf16_f32 v10, v16, v17
	v_cvt_pk_bf16_f32 v11, v18, v19
	v_lshl_add_u64 v[12:13], v[8:9], 0, v[142:143]
	v_cvt_pk_bf16_f32 v8, v20, v21
	v_cvt_pk_bf16_f32 v9, v22, v23
	v_cvt_pk_bf16_f32 v4, v4, v5
	v_cvt_pk_bf16_f32 v5, v6, v7
	v_cvt_pk_bf16_f32 v6, v0, v1
	v_cvt_pk_bf16_f32 v7, v2, v3
	s_and_b64 vcc, exec, s[38:39]
	s_mov_b32 s34, s4
	s_mov_b32 s0, s6
	s_mov_b64 s[14:15], s[10:11]
	s_mov_b64 s[12:13], s[8:9]
	global_store_dwordx4 v[146:147], v[124:127], off
	global_store_dwordx4 v[108:109], v[104:107], off
	global_store_dwordx4 v[92:93], v[88:91], off
	global_store_dwordx4 v[76:77], v[72:75], off
	global_store_dwordx4 v[76:77], v[68:71], off offset:256
	global_store_dwordx4 v[64:65], v[60:63], off
	global_store_dwordx4 v[44:45], v[40:43], off
	global_store_dwordx4 v[28:29], v[24:27], off
	global_store_dwordx4 v[12:13], v[8:11], off
	global_store_dwordx4 v[12:13], v[4:7], off offset:256
	s_cbranch_vccz .LBB0_355
	s_waitcnt vmcnt(0)
	v_readlane_b32 s22, v255, 14
	s_cmpk_gt_u32 s19, 0xff
	v_readlane_b32 s23, v255, 15
	s_mov_b64 s[28:29], s[54:55]
	s_cbranch_scc1 .LBB0_362
	s_barrier
